# loop-edge edits: trip-loop induction updates hoisted into the last MFMA segment + first eight ds_reads of a trip issued ahead of the head's scalar pointer-select block
# baseline (speedup 1.0000x reference)
.LBB0_119:
	s_add_i32 s8, 0, 0x10000
	v_add_u32_e32 v143, s8, v139
	s_add_i32 s31, 0, 0x14000
	ds_read_b128 v[156:159], v143
	ds_read_b128 v[160:163], v143 offset:1024
	ds_read_b128 v[164:167], v143 offset:2048
	ds_read_b128 v[168:171], v143 offset:3072
	v_add_u32_e32 v143, s31, v139
	ds_read_b128 v[172:175], v143
	ds_read_b128 v[176:179], v143 offset:1024
	ds_read_b128 v[180:183], v143 offset:2048
	ds_read_b128 v[184:187], v143 offset:3072
	s_add_u32 s6, s46, 0xfffc0080
	s_addc_u32 s7, s47, -1
	s_cmp_eq_u32 s30, 12
	s_cselect_b32 s19, s12, s7
	s_cselect_b32 s18, s14, s6
	s_cselect_b32 s7, s15, s23
	s_cselect_b32 s6, s16, s17
	v_lshl_add_u64 v[226:227], s[46:47], 0, v[134:135]
	s_add_i32 m0, s13, 0xc000
	ds_read_b128 v[188:191], v142
	ds_read_b128 v[198:201], v142 offset:1024
	ds_read_b128 v[202:205], v142 offset:2048
	ds_read_b128 v[206:209], v142 offset:3072
	ds_read_b128 v[210:213], v142 offset:4096
	ds_read_b128 v[214:217], v142 offset:5120
	ds_read_b128 v[218:221], v142 offset:6144
	ds_read_b128 v[222:225], v142 offset:7168
	global_load_lds_dwordx4 v[226:227], off
	v_lshl_add_u64 v[226:227], s[46:47], 0, v[136:137]
	s_add_i32 m0, s13, 0xe000
	s_nop 0
	global_load_lds_dwordx4 v[226:227], off
	s_waitcnt vmcnt(8)
	s_waitcnt lgkmcnt(0)
	s_barrier
	s_setprio 1
	s_waitcnt lgkmcnt(0)
	v_mfma_f32_16x16x32_bf16 v[124:127], v[156:159], v[188:191], v[124:127]
	v_mfma_f32_16x16x32_bf16 v[120:123], v[164:167], v[188:191], v[120:123]
	v_mfma_f32_16x16x32_bf16 v[108:111], v[156:159], v[202:205], v[108:111]
	v_mfma_f32_16x16x32_bf16 v[104:107], v[164:167], v[202:205], v[104:107]
	v_mfma_f32_16x16x32_bf16 v[92:95], v[156:159], v[210:213], v[92:95]
	v_mfma_f32_16x16x32_bf16 v[88:91], v[164:167], v[210:213], v[88:91]
	v_mfma_f32_16x16x32_bf16 v[76:79], v[156:159], v[218:221], v[76:79]
	v_mfma_f32_16x16x32_bf16 v[72:75], v[164:167], v[218:221], v[72:75]
	v_mfma_f32_16x16x32_bf16 v[124:127], v[160:163], v[198:201], v[124:127]
	v_mfma_f32_16x16x32_bf16 v[120:123], v[168:171], v[198:201], v[120:123]
	v_mfma_f32_16x16x32_bf16 v[108:111], v[160:163], v[206:209], v[108:111]
	v_mfma_f32_16x16x32_bf16 v[104:107], v[168:171], v[206:209], v[104:107]
	v_mfma_f32_16x16x32_bf16 v[92:95], v[160:163], v[214:217], v[92:95]
	v_mfma_f32_16x16x32_bf16 v[88:91], v[168:171], v[214:217], v[88:91]
	v_mfma_f32_16x16x32_bf16 v[76:79], v[160:163], v[222:225], v[76:79]
	v_mfma_f32_16x16x32_bf16 v[72:75], v[168:171], v[222:225], v[72:75]
	s_setprio 0
	s_setprio 1
	v_mfma_f32_16x16x32_bf16 v[116:119], v[172:175], v[188:191], v[116:119]
	v_mfma_f32_16x16x32_bf16 v[112:115], v[180:183], v[188:191], v[112:115]
	v_mfma_f32_16x16x32_bf16 v[100:103], v[172:175], v[202:205], v[100:103]
	v_mfma_f32_16x16x32_bf16 v[96:99], v[180:183], v[202:205], v[96:99]
	v_mfma_f32_16x16x32_bf16 v[84:87], v[172:175], v[210:213], v[84:87]
	v_mfma_f32_16x16x32_bf16 v[80:83], v[180:183], v[210:213], v[80:83]
	v_mfma_f32_16x16x32_bf16 v[68:71], v[172:175], v[218:221], v[68:71]
	v_mfma_f32_16x16x32_bf16 v[64:67], v[180:183], v[218:221], v[64:67]
	v_mfma_f32_16x16x32_bf16 v[116:119], v[176:179], v[198:201], v[116:119]
	v_mfma_f32_16x16x32_bf16 v[112:115], v[184:187], v[198:201], v[112:115]
	v_mfma_f32_16x16x32_bf16 v[100:103], v[176:179], v[206:209], v[100:103]
	v_mfma_f32_16x16x32_bf16 v[96:99], v[184:187], v[206:209], v[96:99]
	v_mfma_f32_16x16x32_bf16 v[84:87], v[176:179], v[214:217], v[84:87]
	v_mfma_f32_16x16x32_bf16 v[80:83], v[184:187], v[214:217], v[80:83]
	v_mfma_f32_16x16x32_bf16 v[68:71], v[176:179], v[222:225], v[68:71]
	v_mfma_f32_16x16x32_bf16 v[64:67], v[184:187], v[222:225], v[64:67]
	s_setprio 0
	s_barrier
	s_add_i32 s8, s8, s0
	v_lshl_add_u64 v[226:227], s[6:7], 0, v[144:145]
	s_mov_b32 m0, s8
	ds_read_b128 v[188:191], v142 offset:16384
	ds_read_b128 v[198:201], v142 offset:17408
	ds_read_b128 v[202:205], v142 offset:18432
	ds_read_b128 v[206:209], v142 offset:19456
	ds_read_b128 v[210:213], v142 offset:20480
	ds_read_b128 v[214:217], v142 offset:21504
	ds_read_b128 v[218:221], v142 offset:22528
	ds_read_b128 v[222:225], v142 offset:23552
	global_load_lds_dwordx4 v[226:227], off
	s_add_i32 m0, s8, 0x2000
	s_add_u32 s8, s6, 0x40000
	v_lshl_add_u64 v[228:229], s[6:7], 0, v[128:129]
	s_addc_u32 s9, s7, 0
	s_add_i32 s31, s31, s0
	global_load_lds_dwordx4 v[228:229], off
	v_lshl_add_u64 v[230:231], s[8:9], 0, v[144:145]
	s_mov_b32 m0, s31
	v_lshl_add_u64 v[232:233], s[18:19], 0, v[130:131]
	global_load_lds_dwordx4 v[230:231], off
	v_lshl_add_u64 v[230:231], s[8:9], 0, v[128:129]
	s_add_i32 m0, s31, 0x2000
	s_nop 0
	global_load_lds_dwordx4 v[230:231], off
	v_lshl_add_u64 v[230:231], s[18:19], 0, v[132:133]
	s_mov_b32 m0, s13
	s_nop 0
	global_load_lds_dwordx4 v[230:231], off
	s_mov_b32 m0, s24
	s_nop 0
	global_load_lds_dwordx4 v[232:233], off
	s_waitcnt vmcnt(8)
	s_waitcnt lgkmcnt(0)
	s_barrier
	s_setprio 1
	s_waitcnt lgkmcnt(0)
	v_mfma_f32_16x16x32_bf16 v[60:63], v[156:159], v[188:191], v[60:63]
	v_mfma_f32_16x16x32_bf16 v[56:59], v[164:167], v[188:191], v[56:59]
	v_mfma_f32_16x16x32_bf16 v[44:47], v[156:159], v[202:205], v[44:47]
	v_mfma_f32_16x16x32_bf16 v[40:43], v[164:167], v[202:205], v[40:43]
	v_mfma_f32_16x16x32_bf16 v[28:31], v[156:159], v[210:213], v[28:31]
	v_mfma_f32_16x16x32_bf16 v[24:27], v[164:167], v[210:213], v[24:27]
	v_mfma_f32_16x16x32_bf16 v[12:15], v[156:159], v[218:221], v[12:15]
	v_mfma_f32_16x16x32_bf16 v[8:11], v[164:167], v[218:221], v[8:11]
	v_mfma_f32_16x16x32_bf16 v[60:63], v[160:163], v[198:201], v[60:63]
	v_mfma_f32_16x16x32_bf16 v[56:59], v[168:171], v[198:201], v[56:59]
	v_mfma_f32_16x16x32_bf16 v[44:47], v[160:163], v[206:209], v[44:47]
	v_mfma_f32_16x16x32_bf16 v[40:43], v[168:171], v[206:209], v[40:43]
	v_mfma_f32_16x16x32_bf16 v[28:31], v[160:163], v[214:217], v[28:31]
	v_mfma_f32_16x16x32_bf16 v[24:27], v[168:171], v[214:217], v[24:27]
	v_mfma_f32_16x16x32_bf16 v[12:15], v[160:163], v[222:225], v[12:15]
	v_mfma_f32_16x16x32_bf16 v[8:11], v[168:171], v[222:225], v[8:11]
	s_setprio 0
	s_setprio 1
	v_mfma_f32_16x16x32_bf16 v[52:55], v[172:175], v[188:191], v[52:55]
	v_mfma_f32_16x16x32_bf16 v[48:51], v[180:183], v[188:191], v[48:51]
	v_mfma_f32_16x16x32_bf16 v[36:39], v[172:175], v[202:205], v[36:39]
	v_mfma_f32_16x16x32_bf16 v[32:35], v[180:183], v[202:205], v[32:35]
	v_mfma_f32_16x16x32_bf16 v[20:23], v[172:175], v[210:213], v[20:23]
	v_mfma_f32_16x16x32_bf16 v[16:19], v[180:183], v[210:213], v[16:19]
	v_mfma_f32_16x16x32_bf16 v[4:7], v[172:175], v[218:221], v[4:7]
	v_mfma_f32_16x16x32_bf16 v[0:3], v[180:183], v[218:221], v[0:3]
	v_mfma_f32_16x16x32_bf16 v[52:55], v[176:179], v[198:201], v[52:55]
	v_mfma_f32_16x16x32_bf16 v[48:51], v[184:187], v[198:201], v[48:51]
	v_mfma_f32_16x16x32_bf16 v[36:39], v[176:179], v[206:209], v[36:39]
	v_mfma_f32_16x16x32_bf16 v[32:35], v[184:187], v[206:209], v[32:35]
	v_mfma_f32_16x16x32_bf16 v[20:23], v[176:179], v[214:217], v[20:23]
	v_mfma_f32_16x16x32_bf16 v[16:19], v[184:187], v[214:217], v[16:19]
	v_mfma_f32_16x16x32_bf16 v[4:7], v[176:179], v[222:225], v[4:7]
	v_mfma_f32_16x16x32_bf16 v[0:3], v[184:187], v[222:225], v[0:3]
	s_setprio 0
	s_barrier
	s_add_i32 s31, 0, 0x18000
	v_add_u32_e32 v143, s31, v139
	s_add_i32 s33, 0, 0x1c000
	ds_read_b128 v[156:159], v143
	ds_read_b128 v[160:163], v143 offset:1024
	ds_read_b128 v[164:167], v143 offset:2048
	ds_read_b128 v[168:171], v143 offset:3072
	v_add_u32_e32 v143, s33, v139
	ds_read_b128 v[172:175], v143
	ds_read_b128 v[176:179], v143 offset:1024
	ds_read_b128 v[180:183], v143 offset:2048
	ds_read_b128 v[184:187], v143 offset:3072
	s_add_u32 s8, s18, 0x40000
	s_addc_u32 s9, s19, 0
	s_mov_b32 m0, s25
	v_lshl_add_u64 v[234:235], s[8:9], 0, v[132:133]
	ds_read_b128 v[188:191], v142 offset:32768
	ds_read_b128 v[198:201], v142 offset:33792
	ds_read_b128 v[202:205], v142 offset:34816
	ds_read_b128 v[206:209], v142 offset:35840
	ds_read_b128 v[210:213], v142 offset:36864
	ds_read_b128 v[214:217], v142 offset:37888
	ds_read_b128 v[218:221], v142 offset:38912
	ds_read_b128 v[222:225], v142 offset:39936
	global_load_lds_dwordx4 v[234:235], off
	v_lshl_add_u64 v[234:235], s[8:9], 0, v[130:131]
	s_mov_b32 m0, s50
	s_nop 0
	global_load_lds_dwordx4 v[234:235], off
	s_waitcnt vmcnt(8)
	s_waitcnt lgkmcnt(0)
	s_barrier
	s_setprio 1
	s_waitcnt lgkmcnt(0)
	v_mfma_f32_16x16x32_bf16 v[124:127], v[156:159], v[188:191], v[124:127]
	v_mfma_f32_16x16x32_bf16 v[120:123], v[164:167], v[188:191], v[120:123]
	v_mfma_f32_16x16x32_bf16 v[108:111], v[156:159], v[202:205], v[108:111]
	v_mfma_f32_16x16x32_bf16 v[104:107], v[164:167], v[202:205], v[104:107]
	v_mfma_f32_16x16x32_bf16 v[92:95], v[156:159], v[210:213], v[92:95]
	v_mfma_f32_16x16x32_bf16 v[88:91], v[164:167], v[210:213], v[88:91]
	v_mfma_f32_16x16x32_bf16 v[76:79], v[156:159], v[218:221], v[76:79]
	v_mfma_f32_16x16x32_bf16 v[72:75], v[164:167], v[218:221], v[72:75]
	v_mfma_f32_16x16x32_bf16 v[124:127], v[160:163], v[198:201], v[124:127]
	v_mfma_f32_16x16x32_bf16 v[120:123], v[168:171], v[198:201], v[120:123]
	v_mfma_f32_16x16x32_bf16 v[108:111], v[160:163], v[206:209], v[108:111]
	v_mfma_f32_16x16x32_bf16 v[104:107], v[168:171], v[206:209], v[104:107]
	v_mfma_f32_16x16x32_bf16 v[92:95], v[160:163], v[214:217], v[92:95]
	v_mfma_f32_16x16x32_bf16 v[88:91], v[168:171], v[214:217], v[88:91]
	v_mfma_f32_16x16x32_bf16 v[76:79], v[160:163], v[222:225], v[76:79]
	v_mfma_f32_16x16x32_bf16 v[72:75], v[168:171], v[222:225], v[72:75]
	s_setprio 0
	s_setprio 1
	v_mfma_f32_16x16x32_bf16 v[116:119], v[172:175], v[188:191], v[116:119]
	v_mfma_f32_16x16x32_bf16 v[112:115], v[180:183], v[188:191], v[112:115]
	v_mfma_f32_16x16x32_bf16 v[100:103], v[172:175], v[202:205], v[100:103]
	v_mfma_f32_16x16x32_bf16 v[96:99], v[180:183], v[202:205], v[96:99]
	v_mfma_f32_16x16x32_bf16 v[84:87], v[172:175], v[210:213], v[84:87]
	v_mfma_f32_16x16x32_bf16 v[80:83], v[180:183], v[210:213], v[80:83]
	v_mfma_f32_16x16x32_bf16 v[68:71], v[172:175], v[218:221], v[68:71]
	v_mfma_f32_16x16x32_bf16 v[64:67], v[180:183], v[218:221], v[64:67]
	v_mfma_f32_16x16x32_bf16 v[116:119], v[176:179], v[198:201], v[116:119]
	v_mfma_f32_16x16x32_bf16 v[112:115], v[184:187], v[198:201], v[112:115]
	v_mfma_f32_16x16x32_bf16 v[100:103], v[176:179], v[206:209], v[100:103]
	v_mfma_f32_16x16x32_bf16 v[96:99], v[184:187], v[206:209], v[96:99]
	v_mfma_f32_16x16x32_bf16 v[84:87], v[176:179], v[214:217], v[84:87]
	v_mfma_f32_16x16x32_bf16 v[80:83], v[184:187], v[214:217], v[80:83]
	v_mfma_f32_16x16x32_bf16 v[68:71], v[176:179], v[222:225], v[68:71]
	v_mfma_f32_16x16x32_bf16 v[64:67], v[184:187], v[222:225], v[64:67]
	s_setprio 0
	s_barrier
	s_add_i32 s8, s31, s0
	v_lshl_add_u64 v[226:227], v[226:227], 0, s[70:71]
	s_mov_b32 m0, s8
	ds_read_b128 v[188:191], v142 offset:49152
	ds_read_b128 v[198:201], v142 offset:50176
	ds_read_b128 v[202:205], v142 offset:51200
	ds_read_b128 v[206:209], v142 offset:52224
	ds_read_b128 v[210:213], v142 offset:53248
	ds_read_b128 v[214:217], v142 offset:54272
	ds_read_b128 v[218:221], v142 offset:55296
	ds_read_b128 v[222:225], v142 offset:56320
	global_load_lds_dwordx4 v[226:227], off
	s_add_i32 m0, s8, 0x2000
	s_add_u32 s6, s6, 0x40080
	v_lshl_add_u64 v[226:227], v[228:229], 0, s[70:71]
	s_addc_u32 s7, s7, 0
	s_add_i32 s8, s33, s0
	global_load_lds_dwordx4 v[226:227], off
	v_lshl_add_u64 v[226:227], s[6:7], 0, v[144:145]
	s_mov_b32 m0, s8
	s_nop 0
	global_load_lds_dwordx4 v[226:227], off
	v_lshl_add_u64 v[226:227], s[6:7], 0, v[128:129]
	s_add_i32 m0, s8, 0x2000
	s_nop 0
	global_load_lds_dwordx4 v[226:227], off
	v_lshl_add_u64 v[226:227], v[230:231], 0, s[70:71]
	s_mov_b32 m0, s51
	s_nop 0
	global_load_lds_dwordx4 v[226:227], off
	v_lshl_add_u64 v[226:227], v[232:233], 0, s[70:71]
	s_mov_b32 m0, s65
	s_nop 0
	global_load_lds_dwordx4 v[226:227], off
	s_waitcnt vmcnt(8)
	s_waitcnt lgkmcnt(0)
	s_barrier
	s_setprio 1
	s_waitcnt lgkmcnt(0)
	v_mfma_f32_16x16x32_bf16 v[60:63], v[156:159], v[188:191], v[60:63]
	v_mfma_f32_16x16x32_bf16 v[56:59], v[164:167], v[188:191], v[56:59]
	v_mfma_f32_16x16x32_bf16 v[44:47], v[156:159], v[202:205], v[44:47]
	v_mfma_f32_16x16x32_bf16 v[40:43], v[164:167], v[202:205], v[40:43]
	v_mfma_f32_16x16x32_bf16 v[28:31], v[156:159], v[210:213], v[28:31]
	v_mfma_f32_16x16x32_bf16 v[24:27], v[164:167], v[210:213], v[24:27]
	v_mfma_f32_16x16x32_bf16 v[12:15], v[156:159], v[218:221], v[12:15]
	v_mfma_f32_16x16x32_bf16 v[8:11], v[164:167], v[218:221], v[8:11]
	v_mfma_f32_16x16x32_bf16 v[60:63], v[160:163], v[198:201], v[60:63]
	v_mfma_f32_16x16x32_bf16 v[56:59], v[168:171], v[198:201], v[56:59]
	v_mfma_f32_16x16x32_bf16 v[44:47], v[160:163], v[206:209], v[44:47]
	v_mfma_f32_16x16x32_bf16 v[40:43], v[168:171], v[206:209], v[40:43]
	v_mfma_f32_16x16x32_bf16 v[28:31], v[160:163], v[214:217], v[28:31]
	v_mfma_f32_16x16x32_bf16 v[24:27], v[168:171], v[214:217], v[24:27]
	v_mfma_f32_16x16x32_bf16 v[12:15], v[160:163], v[222:225], v[12:15]
	v_mfma_f32_16x16x32_bf16 v[8:11], v[168:171], v[222:225], v[8:11]
	s_setprio 0
	s_setprio 1
	v_mfma_f32_16x16x32_bf16 v[52:55], v[172:175], v[188:191], v[52:55]
	s_add_i32 s30, s30, 2
	s_add_u32 s46, s46, 0x100
	s_addc_u32 s47, s47, 0
	s_add_u32 s17, s17, 0x100
	s_addc_u32 s23, s23, 0
	s_cmp_gt_u32 s30, 13
	v_mfma_f32_16x16x32_bf16 v[48:51], v[180:183], v[188:191], v[48:51]
	v_mfma_f32_16x16x32_bf16 v[36:39], v[172:175], v[202:205], v[36:39]
	v_mfma_f32_16x16x32_bf16 v[32:35], v[180:183], v[202:205], v[32:35]
	v_mfma_f32_16x16x32_bf16 v[20:23], v[172:175], v[210:213], v[20:23]
	v_mfma_f32_16x16x32_bf16 v[16:19], v[180:183], v[210:213], v[16:19]
	v_mfma_f32_16x16x32_bf16 v[4:7], v[172:175], v[218:221], v[4:7]
	v_mfma_f32_16x16x32_bf16 v[0:3], v[180:183], v[218:221], v[0:3]
	v_mfma_f32_16x16x32_bf16 v[52:55], v[176:179], v[198:201], v[52:55]
	v_mfma_f32_16x16x32_bf16 v[48:51], v[184:187], v[198:201], v[48:51]
	v_mfma_f32_16x16x32_bf16 v[36:39], v[176:179], v[206:209], v[36:39]
	v_mfma_f32_16x16x32_bf16 v[32:35], v[184:187], v[206:209], v[32:35]
	v_mfma_f32_16x16x32_bf16 v[20:23], v[176:179], v[214:217], v[20:23]
	v_mfma_f32_16x16x32_bf16 v[16:19], v[184:187], v[214:217], v[16:19]
	v_mfma_f32_16x16x32_bf16 v[4:7], v[176:179], v[222:225], v[4:7]
	v_mfma_f32_16x16x32_bf16 v[0:3], v[184:187], v[222:225], v[0:3]
	s_setprio 0
	s_barrier
	s_cbranch_scc0 .LBB0_119
	s_and_b64 vcc, exec, s[4:5]
	s_cbranch_vccz .LBB0_122
	s_barrier

.LBB0_156:
	s_add_i32 s8, 0, 0x10000
	v_add_u32_e32 v142, s8, v139
	s_add_i32 s41, 0, 0x14000
	ds_read_b128 v[156:159], v142
	ds_read_b128 v[160:163], v142 offset:1024
	ds_read_b128 v[164:167], v142 offset:2048
	ds_read_b128 v[168:171], v142 offset:3072
	v_add_u32_e32 v142, s41, v139
	ds_read_b128 v[172:175], v142
	ds_read_b128 v[176:179], v142 offset:1024
	ds_read_b128 v[180:183], v142 offset:2048
	ds_read_b128 v[184:187], v142 offset:3072
	s_add_u32 s6, s48, 0xfffc0080
	s_addc_u32 s7, s49, -1
	s_cmp_eq_u32 s37, 12
	s_cselect_b32 s19, s23, s7
	s_cselect_b32 s18, s24, s6
	s_cselect_b32 s7, s25, s33
	s_cselect_b32 s6, s30, s31
	v_lshl_add_u64 v[142:143], s[48:49], 0, v[134:135]
	s_add_i32 m0, s13, 0xc000
	ds_read_b128 v[188:191], v141
	ds_read_b128 v[198:201], v141 offset:1024
	ds_read_b128 v[202:205], v141 offset:2048
	ds_read_b128 v[206:209], v141 offset:3072
	ds_read_b128 v[210:213], v141 offset:4096
	ds_read_b128 v[214:217], v141 offset:5120
	ds_read_b128 v[218:221], v141 offset:6144
	ds_read_b128 v[222:225], v141 offset:7168
	global_load_lds_dwordx4 v[142:143], off
	v_lshl_add_u64 v[142:143], s[48:49], 0, v[136:137]
	s_add_i32 m0, s13, 0xe000
	s_nop 0
	global_load_lds_dwordx4 v[142:143], off
	s_waitcnt vmcnt(8)
	s_waitcnt lgkmcnt(0)
	s_barrier
	s_setprio 1
	s_waitcnt lgkmcnt(0)
	v_mfma_f32_16x16x32_bf16 v[124:127], v[156:159], v[188:191], v[124:127]
	v_mfma_f32_16x16x32_bf16 v[120:123], v[164:167], v[188:191], v[120:123]
	v_mfma_f32_16x16x32_bf16 v[116:119], v[156:159], v[202:205], v[116:119]
	v_mfma_f32_16x16x32_bf16 v[112:115], v[164:167], v[202:205], v[112:115]
	v_mfma_f32_16x16x32_bf16 v[100:103], v[156:159], v[210:213], v[100:103]
	v_mfma_f32_16x16x32_bf16 v[96:99], v[164:167], v[210:213], v[96:99]
	v_mfma_f32_16x16x32_bf16 v[84:87], v[156:159], v[218:221], v[84:87]
	v_mfma_f32_16x16x32_bf16 v[80:83], v[164:167], v[218:221], v[80:83]
	v_mfma_f32_16x16x32_bf16 v[124:127], v[160:163], v[198:201], v[124:127]
	v_mfma_f32_16x16x32_bf16 v[120:123], v[168:171], v[198:201], v[120:123]
	v_mfma_f32_16x16x32_bf16 v[116:119], v[160:163], v[206:209], v[116:119]
	v_mfma_f32_16x16x32_bf16 v[112:115], v[168:171], v[206:209], v[112:115]
	v_mfma_f32_16x16x32_bf16 v[100:103], v[160:163], v[214:217], v[100:103]
	v_mfma_f32_16x16x32_bf16 v[96:99], v[168:171], v[214:217], v[96:99]
	v_mfma_f32_16x16x32_bf16 v[84:87], v[160:163], v[222:225], v[84:87]
	v_mfma_f32_16x16x32_bf16 v[80:83], v[168:171], v[222:225], v[80:83]
	s_setprio 0
	s_setprio 1
	v_mfma_f32_16x16x32_bf16 v[108:111], v[172:175], v[188:191], v[108:111]
	v_mfma_f32_16x16x32_bf16 v[104:107], v[180:183], v[188:191], v[104:107]
	v_mfma_f32_16x16x32_bf16 v[92:95], v[172:175], v[202:205], v[92:95]
	v_mfma_f32_16x16x32_bf16 v[88:91], v[180:183], v[202:205], v[88:91]
	v_mfma_f32_16x16x32_bf16 v[76:79], v[172:175], v[210:213], v[76:79]
	v_mfma_f32_16x16x32_bf16 v[72:75], v[180:183], v[210:213], v[72:75]
	v_mfma_f32_16x16x32_bf16 v[68:71], v[172:175], v[218:221], v[68:71]
	v_mfma_f32_16x16x32_bf16 v[64:67], v[180:183], v[218:221], v[64:67]
	v_mfma_f32_16x16x32_bf16 v[108:111], v[176:179], v[198:201], v[108:111]
	v_mfma_f32_16x16x32_bf16 v[104:107], v[184:187], v[198:201], v[104:107]
	v_mfma_f32_16x16x32_bf16 v[92:95], v[176:179], v[206:209], v[92:95]
	v_mfma_f32_16x16x32_bf16 v[88:91], v[184:187], v[206:209], v[88:91]
	v_mfma_f32_16x16x32_bf16 v[76:79], v[176:179], v[214:217], v[76:79]
	v_mfma_f32_16x16x32_bf16 v[72:75], v[184:187], v[214:217], v[72:75]
	v_mfma_f32_16x16x32_bf16 v[68:71], v[176:179], v[222:225], v[68:71]
	v_mfma_f32_16x16x32_bf16 v[64:67], v[184:187], v[222:225], v[64:67]
	s_setprio 0
	s_barrier
	s_add_i32 s8, s8, s12
	v_lshl_add_u64 v[142:143], s[6:7], 0, v[144:145]
	s_mov_b32 m0, s8
	ds_read_b128 v[188:191], v141 offset:16384
	ds_read_b128 v[198:201], v141 offset:17408
	ds_read_b128 v[202:205], v141 offset:18432
	ds_read_b128 v[206:209], v141 offset:19456
	ds_read_b128 v[210:213], v141 offset:20480
	ds_read_b128 v[214:217], v141 offset:21504
	ds_read_b128 v[218:221], v141 offset:22528
	ds_read_b128 v[222:225], v141 offset:23552
	global_load_lds_dwordx4 v[142:143], off
	s_add_i32 m0, s8, 0x2000
	s_add_u32 s8, s6, 0x40000
	v_lshl_add_u64 v[226:227], s[6:7], 0, v[132:133]
	s_addc_u32 s9, s7, 0
	s_add_i32 s41, s41, s12
	global_load_lds_dwordx4 v[226:227], off
	v_lshl_add_u64 v[228:229], s[8:9], 0, v[144:145]
	s_mov_b32 m0, s41
	v_lshl_add_u64 v[230:231], s[18:19], 0, v[130:131]
	global_load_lds_dwordx4 v[228:229], off
	v_lshl_add_u64 v[228:229], s[8:9], 0, v[132:133]
	s_add_i32 m0, s41, 0x2000
	s_nop 0
	global_load_lds_dwordx4 v[228:229], off
	v_lshl_add_u64 v[228:229], s[18:19], 0, v[128:129]
	s_mov_b32 m0, s13
	s_nop 0
	global_load_lds_dwordx4 v[228:229], off
	s_mov_b32 m0, s14
	s_nop 0
	global_load_lds_dwordx4 v[230:231], off
	s_waitcnt vmcnt(8)
	s_waitcnt lgkmcnt(0)
	s_barrier
	s_setprio 1
	s_waitcnt lgkmcnt(0)
	v_mfma_f32_16x16x32_bf16 v[60:63], v[156:159], v[188:191], v[60:63]
	v_mfma_f32_16x16x32_bf16 v[56:59], v[164:167], v[188:191], v[56:59]
	v_mfma_f32_16x16x32_bf16 v[52:55], v[156:159], v[202:205], v[52:55]
	v_mfma_f32_16x16x32_bf16 v[48:51], v[164:167], v[202:205], v[48:51]
	v_mfma_f32_16x16x32_bf16 v[36:39], v[156:159], v[210:213], v[36:39]
	v_mfma_f32_16x16x32_bf16 v[32:35], v[164:167], v[210:213], v[32:35]
	v_mfma_f32_16x16x32_bf16 v[20:23], v[156:159], v[218:221], v[20:23]
	v_mfma_f32_16x16x32_bf16 v[16:19], v[164:167], v[218:221], v[16:19]
	v_mfma_f32_16x16x32_bf16 v[60:63], v[160:163], v[198:201], v[60:63]
	v_mfma_f32_16x16x32_bf16 v[56:59], v[168:171], v[198:201], v[56:59]
	v_mfma_f32_16x16x32_bf16 v[52:55], v[160:163], v[206:209], v[52:55]
	v_mfma_f32_16x16x32_bf16 v[48:51], v[168:171], v[206:209], v[48:51]
	v_mfma_f32_16x16x32_bf16 v[36:39], v[160:163], v[214:217], v[36:39]
	v_mfma_f32_16x16x32_bf16 v[32:35], v[168:171], v[214:217], v[32:35]
	v_mfma_f32_16x16x32_bf16 v[20:23], v[160:163], v[222:225], v[20:23]
	v_mfma_f32_16x16x32_bf16 v[16:19], v[168:171], v[222:225], v[16:19]
	s_setprio 0
	s_setprio 1
	v_mfma_f32_16x16x32_bf16 v[44:47], v[172:175], v[188:191], v[44:47]
	v_mfma_f32_16x16x32_bf16 v[40:43], v[180:183], v[188:191], v[40:43]
	v_mfma_f32_16x16x32_bf16 v[28:31], v[172:175], v[202:205], v[28:31]
	v_mfma_f32_16x16x32_bf16 v[24:27], v[180:183], v[202:205], v[24:27]
	v_mfma_f32_16x16x32_bf16 v[12:15], v[172:175], v[210:213], v[12:15]
	v_mfma_f32_16x16x32_bf16 v[8:11], v[180:183], v[210:213], v[8:11]
	v_mfma_f32_16x16x32_bf16 v[4:7], v[172:175], v[218:221], v[4:7]
	v_mfma_f32_16x16x32_bf16 v[0:3], v[180:183], v[218:221], v[0:3]
	v_mfma_f32_16x16x32_bf16 v[44:47], v[176:179], v[198:201], v[44:47]
	v_mfma_f32_16x16x32_bf16 v[40:43], v[184:187], v[198:201], v[40:43]
	v_mfma_f32_16x16x32_bf16 v[28:31], v[176:179], v[206:209], v[28:31]
	v_mfma_f32_16x16x32_bf16 v[24:27], v[184:187], v[206:209], v[24:27]
	v_mfma_f32_16x16x32_bf16 v[12:15], v[176:179], v[214:217], v[12:15]
	v_mfma_f32_16x16x32_bf16 v[8:11], v[184:187], v[214:217], v[8:11]
	v_mfma_f32_16x16x32_bf16 v[4:7], v[176:179], v[222:225], v[4:7]
	v_mfma_f32_16x16x32_bf16 v[0:3], v[184:187], v[222:225], v[0:3]
	s_setprio 0
	s_barrier
	s_add_i32 s41, 0, 0x18000
	v_add_u32_e32 v146, s41, v139
	s_add_i32 s43, 0, 0x1c000
	ds_read_b128 v[156:159], v146
	ds_read_b128 v[160:163], v146 offset:1024
	ds_read_b128 v[164:167], v146 offset:2048
	ds_read_b128 v[168:171], v146 offset:3072
	v_add_u32_e32 v146, s43, v139
	ds_read_b128 v[172:175], v146
	ds_read_b128 v[176:179], v146 offset:1024
	ds_read_b128 v[180:183], v146 offset:2048
	ds_read_b128 v[184:187], v146 offset:3072
	s_add_u32 s8, s18, 0x40000
	s_addc_u32 s9, s19, 0
	s_mov_b32 m0, s15
	v_lshl_add_u64 v[232:233], s[8:9], 0, v[128:129]
	ds_read_b128 v[188:191], v141 offset:32768
	ds_read_b128 v[198:201], v141 offset:33792
	ds_read_b128 v[202:205], v141 offset:34816
	ds_read_b128 v[206:209], v141 offset:35840
	ds_read_b128 v[210:213], v141 offset:36864
	ds_read_b128 v[214:217], v141 offset:37888
	ds_read_b128 v[218:221], v141 offset:38912
	ds_read_b128 v[222:225], v141 offset:39936
	global_load_lds_dwordx4 v[232:233], off
	v_lshl_add_u64 v[232:233], s[8:9], 0, v[130:131]
	s_mov_b32 m0, s16
	s_nop 0
	global_load_lds_dwordx4 v[232:233], off
	s_waitcnt vmcnt(8)
	s_waitcnt lgkmcnt(0)
	s_barrier
	s_setprio 1
	s_waitcnt lgkmcnt(0)
	v_mfma_f32_16x16x32_bf16 v[124:127], v[156:159], v[188:191], v[124:127]
	v_mfma_f32_16x16x32_bf16 v[120:123], v[164:167], v[188:191], v[120:123]
	v_mfma_f32_16x16x32_bf16 v[116:119], v[156:159], v[202:205], v[116:119]
	v_mfma_f32_16x16x32_bf16 v[112:115], v[164:167], v[202:205], v[112:115]
	v_mfma_f32_16x16x32_bf16 v[100:103], v[156:159], v[210:213], v[100:103]
	v_mfma_f32_16x16x32_bf16 v[96:99], v[164:167], v[210:213], v[96:99]
	v_mfma_f32_16x16x32_bf16 v[84:87], v[156:159], v[218:221], v[84:87]
	v_mfma_f32_16x16x32_bf16 v[80:83], v[164:167], v[218:221], v[80:83]
	v_mfma_f32_16x16x32_bf16 v[124:127], v[160:163], v[198:201], v[124:127]
	v_mfma_f32_16x16x32_bf16 v[120:123], v[168:171], v[198:201], v[120:123]
	v_mfma_f32_16x16x32_bf16 v[116:119], v[160:163], v[206:209], v[116:119]
	v_mfma_f32_16x16x32_bf16 v[112:115], v[168:171], v[206:209], v[112:115]
	v_mfma_f32_16x16x32_bf16 v[100:103], v[160:163], v[214:217], v[100:103]
	v_mfma_f32_16x16x32_bf16 v[96:99], v[168:171], v[214:217], v[96:99]
	v_mfma_f32_16x16x32_bf16 v[84:87], v[160:163], v[222:225], v[84:87]
	v_mfma_f32_16x16x32_bf16 v[80:83], v[168:171], v[222:225], v[80:83]
	s_setprio 0
	s_setprio 1
	v_mfma_f32_16x16x32_bf16 v[108:111], v[172:175], v[188:191], v[108:111]
	v_mfma_f32_16x16x32_bf16 v[104:107], v[180:183], v[188:191], v[104:107]
	v_mfma_f32_16x16x32_bf16 v[92:95], v[172:175], v[202:205], v[92:95]
	v_mfma_f32_16x16x32_bf16 v[88:91], v[180:183], v[202:205], v[88:91]
	v_mfma_f32_16x16x32_bf16 v[76:79], v[172:175], v[210:213], v[76:79]
	v_mfma_f32_16x16x32_bf16 v[72:75], v[180:183], v[210:213], v[72:75]
	v_mfma_f32_16x16x32_bf16 v[68:71], v[172:175], v[218:221], v[68:71]
	v_mfma_f32_16x16x32_bf16 v[64:67], v[180:183], v[218:221], v[64:67]
	v_mfma_f32_16x16x32_bf16 v[108:111], v[176:179], v[198:201], v[108:111]
	v_mfma_f32_16x16x32_bf16 v[104:107], v[184:187], v[198:201], v[104:107]
	v_mfma_f32_16x16x32_bf16 v[92:95], v[176:179], v[206:209], v[92:95]
	v_mfma_f32_16x16x32_bf16 v[88:91], v[184:187], v[206:209], v[88:91]
	v_mfma_f32_16x16x32_bf16 v[76:79], v[176:179], v[214:217], v[76:79]
	v_mfma_f32_16x16x32_bf16 v[72:75], v[184:187], v[214:217], v[72:75]
	v_mfma_f32_16x16x32_bf16 v[68:71], v[176:179], v[222:225], v[68:71]
	v_mfma_f32_16x16x32_bf16 v[64:67], v[184:187], v[222:225], v[64:67]
	s_setprio 0
	s_barrier
	s_add_i32 s8, s41, s12
	v_lshl_add_u64 v[142:143], v[142:143], 0, s[70:71]
	s_mov_b32 m0, s8
	ds_read_b128 v[188:191], v141 offset:49152
	ds_read_b128 v[198:201], v141 offset:50176
	ds_read_b128 v[202:205], v141 offset:51200
	ds_read_b128 v[206:209], v141 offset:52224
	ds_read_b128 v[210:213], v141 offset:53248
	ds_read_b128 v[214:217], v141 offset:54272
	ds_read_b128 v[218:221], v141 offset:55296
	ds_read_b128 v[222:225], v141 offset:56320
	global_load_lds_dwordx4 v[142:143], off
	s_add_i32 m0, s8, 0x2000
	s_add_u32 s6, s6, 0x40080
	v_lshl_add_u64 v[142:143], v[226:227], 0, s[70:71]
	s_addc_u32 s7, s7, 0
	s_add_i32 s8, s43, s12
	global_load_lds_dwordx4 v[142:143], off
	v_lshl_add_u64 v[142:143], s[6:7], 0, v[144:145]
	s_mov_b32 m0, s8
	s_nop 0
	global_load_lds_dwordx4 v[142:143], off
	v_lshl_add_u64 v[142:143], s[6:7], 0, v[132:133]
	s_add_i32 m0, s8, 0x2000
	s_nop 0
	global_load_lds_dwordx4 v[142:143], off
	v_lshl_add_u64 v[142:143], v[228:229], 0, s[70:71]
	s_mov_b32 m0, s0
	s_nop 0
	global_load_lds_dwordx4 v[142:143], off
	v_lshl_add_u64 v[142:143], v[230:231], 0, s[70:71]
	s_mov_b32 m0, s17
	s_nop 0
	global_load_lds_dwordx4 v[142:143], off
	s_waitcnt vmcnt(8)
	s_waitcnt lgkmcnt(0)
	s_barrier
	s_setprio 1
	s_waitcnt lgkmcnt(0)
	v_mfma_f32_16x16x32_bf16 v[60:63], v[156:159], v[188:191], v[60:63]
	v_mfma_f32_16x16x32_bf16 v[56:59], v[164:167], v[188:191], v[56:59]
	v_mfma_f32_16x16x32_bf16 v[52:55], v[156:159], v[202:205], v[52:55]
	v_mfma_f32_16x16x32_bf16 v[48:51], v[164:167], v[202:205], v[48:51]
	v_mfma_f32_16x16x32_bf16 v[36:39], v[156:159], v[210:213], v[36:39]
	v_mfma_f32_16x16x32_bf16 v[32:35], v[164:167], v[210:213], v[32:35]
	v_mfma_f32_16x16x32_bf16 v[20:23], v[156:159], v[218:221], v[20:23]
	v_mfma_f32_16x16x32_bf16 v[16:19], v[164:167], v[218:221], v[16:19]
	v_mfma_f32_16x16x32_bf16 v[60:63], v[160:163], v[198:201], v[60:63]
	v_mfma_f32_16x16x32_bf16 v[56:59], v[168:171], v[198:201], v[56:59]
	v_mfma_f32_16x16x32_bf16 v[52:55], v[160:163], v[206:209], v[52:55]
	v_mfma_f32_16x16x32_bf16 v[48:51], v[168:171], v[206:209], v[48:51]
	v_mfma_f32_16x16x32_bf16 v[36:39], v[160:163], v[214:217], v[36:39]
	v_mfma_f32_16x16x32_bf16 v[32:35], v[168:171], v[214:217], v[32:35]
	v_mfma_f32_16x16x32_bf16 v[20:23], v[160:163], v[222:225], v[20:23]
	v_mfma_f32_16x16x32_bf16 v[16:19], v[168:171], v[222:225], v[16:19]
	s_setprio 0
	s_setprio 1
	v_mfma_f32_16x16x32_bf16 v[44:47], v[172:175], v[188:191], v[44:47]
	s_add_i32 s37, s37, 2
	s_add_u32 s48, s48, 0x100
	s_addc_u32 s49, s49, 0
	s_add_u32 s31, s31, 0x100
	s_addc_u32 s33, s33, 0
	s_cmp_gt_u32 s37, 13
	v_mfma_f32_16x16x32_bf16 v[40:43], v[180:183], v[188:191], v[40:43]
	v_mfma_f32_16x16x32_bf16 v[28:31], v[172:175], v[202:205], v[28:31]
	v_mfma_f32_16x16x32_bf16 v[24:27], v[180:183], v[202:205], v[24:27]
	v_mfma_f32_16x16x32_bf16 v[12:15], v[172:175], v[210:213], v[12:15]
	v_mfma_f32_16x16x32_bf16 v[8:11], v[180:183], v[210:213], v[8:11]
	v_mfma_f32_16x16x32_bf16 v[4:7], v[172:175], v[218:221], v[4:7]
	v_mfma_f32_16x16x32_bf16 v[0:3], v[180:183], v[218:221], v[0:3]
	v_mfma_f32_16x16x32_bf16 v[44:47], v[176:179], v[198:201], v[44:47]
	v_mfma_f32_16x16x32_bf16 v[40:43], v[184:187], v[198:201], v[40:43]
	v_mfma_f32_16x16x32_bf16 v[28:31], v[176:179], v[206:209], v[28:31]
	v_mfma_f32_16x16x32_bf16 v[24:27], v[184:187], v[206:209], v[24:27]
	v_mfma_f32_16x16x32_bf16 v[12:15], v[176:179], v[214:217], v[12:15]
	v_mfma_f32_16x16x32_bf16 v[8:11], v[184:187], v[214:217], v[8:11]
	v_mfma_f32_16x16x32_bf16 v[4:7], v[176:179], v[222:225], v[4:7]
	v_mfma_f32_16x16x32_bf16 v[0:3], v[184:187], v[222:225], v[0:3]
	s_setprio 0
	s_barrier
	s_cbranch_scc0 .LBB0_156
	s_and_b64 vcc, exec, s[4:5]
	s_movk_i32 s23, 0xf000
	s_movk_i32 s33, 0xe000
	s_mov_b32 s30, s52
	s_cbranch_vccz .LBB0_159
	s_barrier

.LBB0_409:
	s_add_i32 s8, 0, 0x10000
	v_add_u32_e32 v146, s8, v143
	s_add_i32 s31, 0, 0x14000
	ds_read_b128 v[138:141], v146
	ds_read_b128 v[160:163], v146 offset:1024
	ds_read_b128 v[164:167], v146 offset:2048
	ds_read_b128 v[168:171], v146 offset:3072
	v_add_u32_e32 v146, s31, v143
	ds_read_b128 v[172:175], v146
	ds_read_b128 v[176:179], v146 offset:1024
	ds_read_b128 v[180:183], v146 offset:2048
	ds_read_b128 v[184:187], v146 offset:3072
	s_add_u32 s6, s46, 0xfffc0080
	s_addc_u32 s7, s47, -1
	s_cmp_eq_u32 s30, 12
	s_cselect_b32 s19, s12, s7
	s_cselect_b32 s18, s14, s6
	s_cselect_b32 s7, s15, s23
	s_cselect_b32 s6, s16, s17
	v_lshl_add_u64 v[146:147], s[46:47], 0, v[134:135]
	s_add_i32 m0, s25, 0xc000
	ds_read_b128 v[188:191], v158
	ds_read_b128 v[198:201], v158 offset:1024
	ds_read_b128 v[202:205], v158 offset:2048
	ds_read_b128 v[206:209], v158 offset:3072
	ds_read_b128 v[210:213], v158 offset:4096
	ds_read_b128 v[214:217], v158 offset:5120
	ds_read_b128 v[218:221], v158 offset:6144
	ds_read_b128 v[222:225], v158 offset:7168
	global_load_lds_dwordx4 v[146:147], off
	v_lshl_add_u64 v[146:147], s[46:47], 0, v[136:137]
	s_add_i32 m0, s25, 0xe000
	s_nop 0
	global_load_lds_dwordx4 v[146:147], off
	s_waitcnt vmcnt(8)
	s_waitcnt lgkmcnt(0)
	s_barrier
	s_setprio 1
	s_waitcnt lgkmcnt(0)
	v_mfma_f32_16x16x32_bf16 v[124:127], v[138:141], v[188:191], v[124:127]
	v_mfma_f32_16x16x32_bf16 v[120:123], v[164:167], v[188:191], v[120:123]
	v_mfma_f32_16x16x32_bf16 v[108:111], v[138:141], v[202:205], v[108:111]
	v_mfma_f32_16x16x32_bf16 v[104:107], v[164:167], v[202:205], v[104:107]
	v_mfma_f32_16x16x32_bf16 v[92:95], v[138:141], v[210:213], v[92:95]
	v_mfma_f32_16x16x32_bf16 v[88:91], v[164:167], v[210:213], v[88:91]
	v_mfma_f32_16x16x32_bf16 v[76:79], v[138:141], v[218:221], v[76:79]
	v_mfma_f32_16x16x32_bf16 v[72:75], v[164:167], v[218:221], v[72:75]
	v_mfma_f32_16x16x32_bf16 v[124:127], v[160:163], v[198:201], v[124:127]
	v_mfma_f32_16x16x32_bf16 v[120:123], v[168:171], v[198:201], v[120:123]
	v_mfma_f32_16x16x32_bf16 v[108:111], v[160:163], v[206:209], v[108:111]
	v_mfma_f32_16x16x32_bf16 v[104:107], v[168:171], v[206:209], v[104:107]
	v_mfma_f32_16x16x32_bf16 v[92:95], v[160:163], v[214:217], v[92:95]
	v_mfma_f32_16x16x32_bf16 v[88:91], v[168:171], v[214:217], v[88:91]
	v_mfma_f32_16x16x32_bf16 v[76:79], v[160:163], v[222:225], v[76:79]
	v_mfma_f32_16x16x32_bf16 v[72:75], v[168:171], v[222:225], v[72:75]
	s_setprio 0
	s_setprio 1
	v_mfma_f32_16x16x32_bf16 v[116:119], v[172:175], v[188:191], v[116:119]
	v_mfma_f32_16x16x32_bf16 v[112:115], v[180:183], v[188:191], v[112:115]
	v_mfma_f32_16x16x32_bf16 v[100:103], v[172:175], v[202:205], v[100:103]
	v_mfma_f32_16x16x32_bf16 v[96:99], v[180:183], v[202:205], v[96:99]
	v_mfma_f32_16x16x32_bf16 v[84:87], v[172:175], v[210:213], v[84:87]
	v_mfma_f32_16x16x32_bf16 v[80:83], v[180:183], v[210:213], v[80:83]
	v_mfma_f32_16x16x32_bf16 v[68:71], v[172:175], v[218:221], v[68:71]
	v_mfma_f32_16x16x32_bf16 v[64:67], v[180:183], v[218:221], v[64:67]
	v_mfma_f32_16x16x32_bf16 v[116:119], v[176:179], v[198:201], v[116:119]
	v_mfma_f32_16x16x32_bf16 v[112:115], v[184:187], v[198:201], v[112:115]
	v_mfma_f32_16x16x32_bf16 v[100:103], v[176:179], v[206:209], v[100:103]
	v_mfma_f32_16x16x32_bf16 v[96:99], v[184:187], v[206:209], v[96:99]
	v_mfma_f32_16x16x32_bf16 v[84:87], v[176:179], v[214:217], v[84:87]
	v_mfma_f32_16x16x32_bf16 v[80:83], v[184:187], v[214:217], v[80:83]
	v_mfma_f32_16x16x32_bf16 v[68:71], v[176:179], v[222:225], v[68:71]
	v_mfma_f32_16x16x32_bf16 v[64:67], v[184:187], v[222:225], v[64:67]
	s_setprio 0
	s_barrier
	s_add_i32 s8, s8, s0
	v_lshl_add_u64 v[146:147], s[6:7], 0, v[144:145]
	s_mov_b32 m0, s8
	ds_read_b128 v[188:191], v158 offset:16384
	ds_read_b128 v[198:201], v158 offset:17408
	ds_read_b128 v[202:205], v158 offset:18432
	ds_read_b128 v[206:209], v158 offset:19456
	ds_read_b128 v[210:213], v158 offset:20480
	ds_read_b128 v[214:217], v158 offset:21504
	ds_read_b128 v[218:221], v158 offset:22528
	ds_read_b128 v[222:225], v158 offset:23552
	global_load_lds_dwordx4 v[146:147], off
	s_add_i32 m0, s8, 0x2000
	s_add_u32 s8, s6, 0x40000
	v_lshl_add_u64 v[154:155], s[6:7], 0, v[128:129]
	s_addc_u32 s9, s7, 0
	s_add_i32 s31, s31, s0
	global_load_lds_dwordx4 v[154:155], off
	v_lshl_add_u64 v[226:227], s[8:9], 0, v[144:145]
	s_mov_b32 m0, s31
	v_lshl_add_u64 v[228:229], s[18:19], 0, v[130:131]
	global_load_lds_dwordx4 v[226:227], off
	v_lshl_add_u64 v[226:227], s[8:9], 0, v[128:129]
	s_add_i32 m0, s31, 0x2000
	s_nop 0
	global_load_lds_dwordx4 v[226:227], off
	v_lshl_add_u64 v[226:227], s[18:19], 0, v[132:133]
	s_mov_b32 m0, s25
	s_nop 0
	global_load_lds_dwordx4 v[226:227], off
	s_mov_b32 m0, s50
	s_nop 0
	global_load_lds_dwordx4 v[228:229], off
	s_waitcnt vmcnt(8)
	s_waitcnt lgkmcnt(0)
	s_barrier
	s_setprio 1
	s_waitcnt lgkmcnt(0)
	v_mfma_f32_16x16x32_bf16 v[60:63], v[138:141], v[188:191], v[60:63]
	v_mfma_f32_16x16x32_bf16 v[56:59], v[164:167], v[188:191], v[56:59]
	v_mfma_f32_16x16x32_bf16 v[52:55], v[138:141], v[202:205], v[52:55]
	v_mfma_f32_16x16x32_bf16 v[44:47], v[164:167], v[202:205], v[44:47]
	v_mfma_f32_16x16x32_bf16 v[32:35], v[138:141], v[210:213], v[32:35]
	v_mfma_f32_16x16x32_bf16 v[24:27], v[164:167], v[210:213], v[24:27]
	v_mfma_f32_16x16x32_bf16 v[20:23], v[138:141], v[218:221], v[20:23]
	v_mfma_f32_16x16x32_bf16 v[12:15], v[164:167], v[218:221], v[12:15]
	v_mfma_f32_16x16x32_bf16 v[60:63], v[160:163], v[198:201], v[60:63]
	v_mfma_f32_16x16x32_bf16 v[56:59], v[168:171], v[198:201], v[56:59]
	v_mfma_f32_16x16x32_bf16 v[52:55], v[160:163], v[206:209], v[52:55]
	v_mfma_f32_16x16x32_bf16 v[44:47], v[168:171], v[206:209], v[44:47]
	v_mfma_f32_16x16x32_bf16 v[32:35], v[160:163], v[214:217], v[32:35]
	v_mfma_f32_16x16x32_bf16 v[24:27], v[168:171], v[214:217], v[24:27]
	v_mfma_f32_16x16x32_bf16 v[20:23], v[160:163], v[222:225], v[20:23]
	v_mfma_f32_16x16x32_bf16 v[12:15], v[168:171], v[222:225], v[12:15]
	s_setprio 0
	s_setprio 1
	v_mfma_f32_16x16x32_bf16 v[48:51], v[172:175], v[188:191], v[48:51]
	v_mfma_f32_16x16x32_bf16 v[40:43], v[180:183], v[188:191], v[40:43]
	v_mfma_f32_16x16x32_bf16 v[36:39], v[172:175], v[202:205], v[36:39]
	v_mfma_f32_16x16x32_bf16 v[28:31], v[180:183], v[202:205], v[28:31]
	v_mfma_f32_16x16x32_bf16 v[16:19], v[172:175], v[210:213], v[16:19]
	v_mfma_f32_16x16x32_bf16 v[8:11], v[180:183], v[210:213], v[8:11]
	v_mfma_f32_16x16x32_bf16 v[4:7], v[172:175], v[218:221], v[4:7]
	v_mfma_f32_16x16x32_bf16 v[0:3], v[180:183], v[218:221], v[0:3]
	v_mfma_f32_16x16x32_bf16 v[48:51], v[176:179], v[198:201], v[48:51]
	v_mfma_f32_16x16x32_bf16 v[40:43], v[184:187], v[198:201], v[40:43]
	v_mfma_f32_16x16x32_bf16 v[36:39], v[176:179], v[206:209], v[36:39]
	v_mfma_f32_16x16x32_bf16 v[28:31], v[184:187], v[206:209], v[28:31]
	v_mfma_f32_16x16x32_bf16 v[16:19], v[176:179], v[214:217], v[16:19]
	v_mfma_f32_16x16x32_bf16 v[8:11], v[184:187], v[214:217], v[8:11]
	v_mfma_f32_16x16x32_bf16 v[4:7], v[176:179], v[222:225], v[4:7]
	v_mfma_f32_16x16x32_bf16 v[0:3], v[184:187], v[222:225], v[0:3]
	s_setprio 0
	s_barrier
	s_add_i32 s31, 0, 0x18000
	v_add_u32_e32 v159, s31, v143
	s_add_i32 s33, 0, 0x1c000
	ds_read_b128 v[138:141], v159
	ds_read_b128 v[160:163], v159 offset:1024
	ds_read_b128 v[164:167], v159 offset:2048
	ds_read_b128 v[168:171], v159 offset:3072
	v_add_u32_e32 v159, s33, v143
	ds_read_b128 v[172:175], v159
	ds_read_b128 v[176:179], v159 offset:1024
	ds_read_b128 v[180:183], v159 offset:2048
	ds_read_b128 v[184:187], v159 offset:3072
	s_add_u32 s8, s18, 0x40000
	s_addc_u32 s9, s19, 0
	s_mov_b32 m0, s51
	v_lshl_add_u64 v[230:231], s[8:9], 0, v[132:133]
	ds_read_b128 v[188:191], v158 offset:32768
	ds_read_b128 v[198:201], v158 offset:33792
	ds_read_b128 v[202:205], v158 offset:34816
	ds_read_b128 v[206:209], v158 offset:35840
	ds_read_b128 v[210:213], v158 offset:36864
	ds_read_b128 v[214:217], v158 offset:37888
	ds_read_b128 v[218:221], v158 offset:38912
	ds_read_b128 v[222:225], v158 offset:39936
	global_load_lds_dwordx4 v[230:231], off
	v_lshl_add_u64 v[230:231], s[8:9], 0, v[130:131]
	s_mov_b32 m0, s64
	s_nop 0
	global_load_lds_dwordx4 v[230:231], off
	s_waitcnt vmcnt(8)
	s_waitcnt lgkmcnt(0)
	s_barrier
	s_setprio 1
	s_waitcnt lgkmcnt(0)
	v_mfma_f32_16x16x32_bf16 v[124:127], v[138:141], v[188:191], v[124:127]
	v_mfma_f32_16x16x32_bf16 v[120:123], v[164:167], v[188:191], v[120:123]
	v_mfma_f32_16x16x32_bf16 v[108:111], v[138:141], v[202:205], v[108:111]
	v_mfma_f32_16x16x32_bf16 v[104:107], v[164:167], v[202:205], v[104:107]
	v_mfma_f32_16x16x32_bf16 v[92:95], v[138:141], v[210:213], v[92:95]
	v_mfma_f32_16x16x32_bf16 v[88:91], v[164:167], v[210:213], v[88:91]
	v_mfma_f32_16x16x32_bf16 v[76:79], v[138:141], v[218:221], v[76:79]
	v_mfma_f32_16x16x32_bf16 v[72:75], v[164:167], v[218:221], v[72:75]
	v_mfma_f32_16x16x32_bf16 v[124:127], v[160:163], v[198:201], v[124:127]
	v_mfma_f32_16x16x32_bf16 v[120:123], v[168:171], v[198:201], v[120:123]
	v_mfma_f32_16x16x32_bf16 v[108:111], v[160:163], v[206:209], v[108:111]
	v_mfma_f32_16x16x32_bf16 v[104:107], v[168:171], v[206:209], v[104:107]
	v_mfma_f32_16x16x32_bf16 v[92:95], v[160:163], v[214:217], v[92:95]
	v_mfma_f32_16x16x32_bf16 v[88:91], v[168:171], v[214:217], v[88:91]
	v_mfma_f32_16x16x32_bf16 v[76:79], v[160:163], v[222:225], v[76:79]
	v_mfma_f32_16x16x32_bf16 v[72:75], v[168:171], v[222:225], v[72:75]
	s_setprio 0
	s_setprio 1
	v_mfma_f32_16x16x32_bf16 v[116:119], v[172:175], v[188:191], v[116:119]
	v_mfma_f32_16x16x32_bf16 v[112:115], v[180:183], v[188:191], v[112:115]
	v_mfma_f32_16x16x32_bf16 v[100:103], v[172:175], v[202:205], v[100:103]
	v_mfma_f32_16x16x32_bf16 v[96:99], v[180:183], v[202:205], v[96:99]
	v_mfma_f32_16x16x32_bf16 v[84:87], v[172:175], v[210:213], v[84:87]
	v_mfma_f32_16x16x32_bf16 v[80:83], v[180:183], v[210:213], v[80:83]
	v_mfma_f32_16x16x32_bf16 v[68:71], v[172:175], v[218:221], v[68:71]
	v_mfma_f32_16x16x32_bf16 v[64:67], v[180:183], v[218:221], v[64:67]
	v_mfma_f32_16x16x32_bf16 v[116:119], v[176:179], v[198:201], v[116:119]
	v_mfma_f32_16x16x32_bf16 v[112:115], v[184:187], v[198:201], v[112:115]
	v_mfma_f32_16x16x32_bf16 v[100:103], v[176:179], v[206:209], v[100:103]
	v_mfma_f32_16x16x32_bf16 v[96:99], v[184:187], v[206:209], v[96:99]
	v_mfma_f32_16x16x32_bf16 v[84:87], v[176:179], v[214:217], v[84:87]
	v_mfma_f32_16x16x32_bf16 v[80:83], v[184:187], v[214:217], v[80:83]
	v_mfma_f32_16x16x32_bf16 v[68:71], v[176:179], v[222:225], v[68:71]
	v_mfma_f32_16x16x32_bf16 v[64:67], v[184:187], v[222:225], v[64:67]
	s_setprio 0
	s_barrier
	s_add_i32 s8, s31, s0
	v_lshl_add_u64 v[146:147], v[146:147], 0, s[70:71]
	s_mov_b32 m0, s8
	ds_read_b128 v[188:191], v158 offset:49152
	ds_read_b128 v[198:201], v158 offset:50176
	ds_read_b128 v[202:205], v158 offset:51200
	ds_read_b128 v[206:209], v158 offset:52224
	ds_read_b128 v[210:213], v158 offset:53248
	ds_read_b128 v[214:217], v158 offset:54272
	ds_read_b128 v[218:221], v158 offset:55296
	ds_read_b128 v[222:225], v158 offset:56320
	global_load_lds_dwordx4 v[146:147], off
	s_add_i32 m0, s8, 0x2000
	s_add_u32 s6, s6, 0x40080
	v_lshl_add_u64 v[146:147], v[154:155], 0, s[70:71]
	s_addc_u32 s7, s7, 0
	s_add_i32 s8, s33, s0
	global_load_lds_dwordx4 v[146:147], off
	v_lshl_add_u64 v[146:147], s[6:7], 0, v[144:145]
	s_mov_b32 m0, s8
	s_nop 0
	global_load_lds_dwordx4 v[146:147], off
	v_lshl_add_u64 v[146:147], s[6:7], 0, v[128:129]
	s_add_i32 m0, s8, 0x2000
	s_nop 0
	global_load_lds_dwordx4 v[146:147], off
	v_lshl_add_u64 v[146:147], v[226:227], 0, s[70:71]
	s_mov_b32 m0, s65
	s_nop 0
	global_load_lds_dwordx4 v[146:147], off
	v_lshl_add_u64 v[146:147], v[228:229], 0, s[70:71]
	s_mov_b32 m0, s68
	s_nop 0
	global_load_lds_dwordx4 v[146:147], off
	s_waitcnt vmcnt(8)
	s_waitcnt lgkmcnt(0)
	s_barrier
	s_setprio 1
	s_waitcnt lgkmcnt(0)
	v_mfma_f32_16x16x32_bf16 v[60:63], v[138:141], v[188:191], v[60:63]
	v_mfma_f32_16x16x32_bf16 v[56:59], v[164:167], v[188:191], v[56:59]
	v_mfma_f32_16x16x32_bf16 v[52:55], v[138:141], v[202:205], v[52:55]
	v_mfma_f32_16x16x32_bf16 v[44:47], v[164:167], v[202:205], v[44:47]
	v_mfma_f32_16x16x32_bf16 v[32:35], v[138:141], v[210:213], v[32:35]
	v_mfma_f32_16x16x32_bf16 v[24:27], v[164:167], v[210:213], v[24:27]
	v_mfma_f32_16x16x32_bf16 v[20:23], v[138:141], v[218:221], v[20:23]
	v_mfma_f32_16x16x32_bf16 v[12:15], v[164:167], v[218:221], v[12:15]
	v_mfma_f32_16x16x32_bf16 v[60:63], v[160:163], v[198:201], v[60:63]
	v_mfma_f32_16x16x32_bf16 v[56:59], v[168:171], v[198:201], v[56:59]
	v_mfma_f32_16x16x32_bf16 v[52:55], v[160:163], v[206:209], v[52:55]
	v_mfma_f32_16x16x32_bf16 v[44:47], v[168:171], v[206:209], v[44:47]
	v_mfma_f32_16x16x32_bf16 v[32:35], v[160:163], v[214:217], v[32:35]
	v_mfma_f32_16x16x32_bf16 v[24:27], v[168:171], v[214:217], v[24:27]
	v_mfma_f32_16x16x32_bf16 v[20:23], v[160:163], v[222:225], v[20:23]
	v_mfma_f32_16x16x32_bf16 v[12:15], v[168:171], v[222:225], v[12:15]
	s_setprio 0
	s_setprio 1
	v_mfma_f32_16x16x32_bf16 v[48:51], v[172:175], v[188:191], v[48:51]
	s_add_i32 s30, s30, 2
	s_add_u32 s46, s46, 0x100
	s_addc_u32 s47, s47, 0
	s_add_u32 s17, s17, 0x100
	s_addc_u32 s23, s23, 0
	s_cmp_gt_u32 s30, 13
	v_mfma_f32_16x16x32_bf16 v[40:43], v[180:183], v[188:191], v[40:43]
	v_mfma_f32_16x16x32_bf16 v[36:39], v[172:175], v[202:205], v[36:39]
	v_mfma_f32_16x16x32_bf16 v[28:31], v[180:183], v[202:205], v[28:31]
	v_mfma_f32_16x16x32_bf16 v[16:19], v[172:175], v[210:213], v[16:19]
	v_mfma_f32_16x16x32_bf16 v[8:11], v[180:183], v[210:213], v[8:11]
	v_mfma_f32_16x16x32_bf16 v[4:7], v[172:175], v[218:221], v[4:7]
	v_mfma_f32_16x16x32_bf16 v[0:3], v[180:183], v[218:221], v[0:3]
	v_mfma_f32_16x16x32_bf16 v[48:51], v[176:179], v[198:201], v[48:51]
	v_mfma_f32_16x16x32_bf16 v[40:43], v[184:187], v[198:201], v[40:43]
	v_mfma_f32_16x16x32_bf16 v[36:39], v[176:179], v[206:209], v[36:39]
	v_mfma_f32_16x16x32_bf16 v[28:31], v[184:187], v[206:209], v[28:31]
	v_mfma_f32_16x16x32_bf16 v[16:19], v[176:179], v[214:217], v[16:19]
	v_mfma_f32_16x16x32_bf16 v[8:11], v[184:187], v[214:217], v[8:11]
	v_mfma_f32_16x16x32_bf16 v[4:7], v[176:179], v[222:225], v[4:7]
	v_mfma_f32_16x16x32_bf16 v[0:3], v[184:187], v[222:225], v[0:3]
	s_setprio 0
	s_barrier
	s_cbranch_scc0 .LBB0_409
	s_and_b64 vcc, exec, s[4:5]
	s_movk_i32 s23, 0xf000
	s_mov_b32 s30, s52
	s_cbranch_vccz .LBB0_412
	s_barrier

.LBB0_741:
	s_add_i32 s16, 0, 0x10000
	v_add_u32_e32 v146, s16, v142
	s_add_i32 s17, 0, 0x14000
	ds_read_b128 v[156:159], v146
	ds_read_b128 v[160:163], v146 offset:1024
	ds_read_b128 v[164:167], v146 offset:2048
	ds_read_b128 v[168:171], v146 offset:3072
	v_add_u32_e32 v146, s17, v142
	ds_read_b128 v[172:175], v146
	ds_read_b128 v[176:179], v146 offset:1024
	ds_read_b128 v[180:183], v146 offset:2048
	ds_read_b128 v[184:187], v146 offset:3072
	s_add_u32 s6, s2, s40
	s_addc_u32 s7, s3, s41
	s_add_u32 s6, s6, 0x100
	s_addc_u32 s7, s7, 0
	s_add_u32 s8, s13, s40
	s_addc_u32 s9, s14, s41
	s_cmpk_eq_i32 s40, 0x700
	s_cselect_b32 s19, s5, s7
	s_cselect_b32 s18, s11, s6
	s_cselect_b32 s7, s43, s9
	s_cselect_b32 s6, s42, s8
	v_lshl_add_u64 v[146:147], v[138:139], 0, s[40:41]
	s_add_i32 m0, s51, 0xc000
	ds_read_b128 v[188:191], v143
	ds_read_b128 v[202:205], v143 offset:1024
	ds_read_b128 v[206:209], v143 offset:2048
	ds_read_b128 v[210:213], v143 offset:3072
	ds_read_b128 v[214:217], v143 offset:4096
	ds_read_b128 v[218:221], v143 offset:5120
	ds_read_b128 v[222:225], v143 offset:6144
	ds_read_b128 v[226:229], v143 offset:7168
	global_load_lds_dwordx4 v[146:147], off
	v_lshl_add_u64 v[146:147], v[140:141], 0, s[40:41]
	s_add_i32 m0, s51, 0xe000
	s_nop 0
	global_load_lds_dwordx4 v[146:147], off
	s_waitcnt vmcnt(8)
	s_waitcnt lgkmcnt(0)
	s_barrier
	s_setprio 1
	s_waitcnt lgkmcnt(0)
	v_mfma_f32_16x16x32_bf16 v[124:127], v[156:159], v[188:191], v[124:127]
	v_mfma_f32_16x16x32_bf16 v[120:123], v[164:167], v[188:191], v[120:123]
	v_mfma_f32_16x16x32_bf16 v[108:111], v[156:159], v[206:209], v[108:111]
	v_mfma_f32_16x16x32_bf16 v[104:107], v[164:167], v[206:209], v[104:107]
	v_mfma_f32_16x16x32_bf16 v[100:103], v[156:159], v[214:217], v[100:103]
	v_mfma_f32_16x16x32_bf16 v[92:95], v[164:167], v[214:217], v[92:95]
	v_mfma_f32_16x16x32_bf16 v[84:87], v[156:159], v[222:225], v[84:87]
	v_mfma_f32_16x16x32_bf16 v[76:79], v[164:167], v[222:225], v[76:79]
	v_mfma_f32_16x16x32_bf16 v[124:127], v[160:163], v[202:205], v[124:127]
	v_mfma_f32_16x16x32_bf16 v[120:123], v[168:171], v[202:205], v[120:123]
	v_mfma_f32_16x16x32_bf16 v[108:111], v[160:163], v[210:213], v[108:111]
	v_mfma_f32_16x16x32_bf16 v[104:107], v[168:171], v[210:213], v[104:107]
	v_mfma_f32_16x16x32_bf16 v[100:103], v[160:163], v[218:221], v[100:103]
	v_mfma_f32_16x16x32_bf16 v[92:95], v[168:171], v[218:221], v[92:95]
	v_mfma_f32_16x16x32_bf16 v[84:87], v[160:163], v[226:229], v[84:87]
	v_mfma_f32_16x16x32_bf16 v[76:79], v[168:171], v[226:229], v[76:79]
	s_setprio 0
	s_setprio 1
	v_mfma_f32_16x16x32_bf16 v[116:119], v[172:175], v[188:191], v[116:119]
	v_mfma_f32_16x16x32_bf16 v[112:115], v[180:183], v[188:191], v[112:115]
	v_mfma_f32_16x16x32_bf16 v[96:99], v[172:175], v[206:209], v[96:99]
	v_mfma_f32_16x16x32_bf16 v[88:91], v[180:183], v[206:209], v[88:91]
	v_mfma_f32_16x16x32_bf16 v[80:83], v[172:175], v[214:217], v[80:83]
	v_mfma_f32_16x16x32_bf16 v[72:75], v[180:183], v[214:217], v[72:75]
	v_mfma_f32_16x16x32_bf16 v[68:71], v[172:175], v[222:225], v[68:71]
	v_mfma_f32_16x16x32_bf16 v[64:67], v[180:183], v[222:225], v[64:67]
	v_mfma_f32_16x16x32_bf16 v[116:119], v[176:179], v[202:205], v[116:119]
	v_mfma_f32_16x16x32_bf16 v[112:115], v[184:187], v[202:205], v[112:115]
	v_mfma_f32_16x16x32_bf16 v[96:99], v[176:179], v[210:213], v[96:99]
	v_mfma_f32_16x16x32_bf16 v[88:91], v[184:187], v[210:213], v[88:91]
	v_mfma_f32_16x16x32_bf16 v[80:83], v[176:179], v[218:221], v[80:83]
	v_mfma_f32_16x16x32_bf16 v[72:75], v[184:187], v[218:221], v[72:75]
	v_mfma_f32_16x16x32_bf16 v[68:71], v[176:179], v[226:229], v[68:71]
	v_mfma_f32_16x16x32_bf16 v[64:67], v[184:187], v[226:229], v[64:67]
	s_setprio 0
	s_barrier
	s_add_i32 s8, s16, s50
	v_lshl_add_u64 v[146:147], s[6:7], 0, v[144:145]
	s_mov_b32 m0, s8
	ds_read_b128 v[188:191], v143 offset:16384
	ds_read_b128 v[202:205], v143 offset:17408
	ds_read_b128 v[206:209], v143 offset:18432
	ds_read_b128 v[210:213], v143 offset:19456
	ds_read_b128 v[214:217], v143 offset:20480
	ds_read_b128 v[218:221], v143 offset:21504
	ds_read_b128 v[222:225], v143 offset:22528
	ds_read_b128 v[226:229], v143 offset:23552
	global_load_lds_dwordx4 v[146:147], off
	s_add_i32 m0, s8, 0x2000
	s_add_u32 s8, s6, 0x40000
	v_lshl_add_u64 v[154:155], s[6:7], 0, v[128:129]
	s_addc_u32 s9, s7, 0
	s_add_i32 s16, s17, s50
	global_load_lds_dwordx4 v[154:155], off
	v_lshl_add_u64 v[230:231], s[8:9], 0, v[144:145]
	s_mov_b32 m0, s16
	v_lshl_add_u64 v[232:233], s[18:19], 0, v[130:131]
	global_load_lds_dwordx4 v[230:231], off
	v_lshl_add_u64 v[230:231], s[8:9], 0, v[128:129]
	s_add_i32 m0, s16, 0x2000
	s_nop 0
	global_load_lds_dwordx4 v[230:231], off
	v_lshl_add_u64 v[230:231], s[18:19], 0, v[132:133]
	s_mov_b32 m0, s51
	s_nop 0
	global_load_lds_dwordx4 v[230:231], off
	s_mov_b32 m0, s64
	s_nop 0
	global_load_lds_dwordx4 v[232:233], off
	s_waitcnt vmcnt(8)
	s_waitcnt lgkmcnt(0)
	s_barrier
	s_setprio 1
	s_waitcnt lgkmcnt(0)
	v_mfma_f32_16x16x32_bf16 v[60:63], v[156:159], v[188:191], v[60:63]
	v_mfma_f32_16x16x32_bf16 v[56:59], v[164:167], v[188:191], v[56:59]
	v_mfma_f32_16x16x32_bf16 v[52:55], v[156:159], v[206:209], v[52:55]
	v_mfma_f32_16x16x32_bf16 v[44:47], v[164:167], v[206:209], v[44:47]
	v_mfma_f32_16x16x32_bf16 v[36:39], v[156:159], v[214:217], v[36:39]
	v_mfma_f32_16x16x32_bf16 v[28:31], v[164:167], v[214:217], v[28:31]
	v_mfma_f32_16x16x32_bf16 v[20:23], v[156:159], v[222:225], v[20:23]
	v_mfma_f32_16x16x32_bf16 v[12:15], v[164:167], v[222:225], v[12:15]
	v_mfma_f32_16x16x32_bf16 v[60:63], v[160:163], v[202:205], v[60:63]
	v_mfma_f32_16x16x32_bf16 v[56:59], v[168:171], v[202:205], v[56:59]
	v_mfma_f32_16x16x32_bf16 v[52:55], v[160:163], v[210:213], v[52:55]
	v_mfma_f32_16x16x32_bf16 v[44:47], v[168:171], v[210:213], v[44:47]
	v_mfma_f32_16x16x32_bf16 v[36:39], v[160:163], v[218:221], v[36:39]
	v_mfma_f32_16x16x32_bf16 v[28:31], v[168:171], v[218:221], v[28:31]
	v_mfma_f32_16x16x32_bf16 v[20:23], v[160:163], v[226:229], v[20:23]
	v_mfma_f32_16x16x32_bf16 v[12:15], v[168:171], v[226:229], v[12:15]
	s_setprio 0
	s_setprio 1
	v_mfma_f32_16x16x32_bf16 v[48:51], v[172:175], v[188:191], v[48:51]
	v_mfma_f32_16x16x32_bf16 v[40:43], v[180:183], v[188:191], v[40:43]
	v_mfma_f32_16x16x32_bf16 v[32:35], v[172:175], v[206:209], v[32:35]
	v_mfma_f32_16x16x32_bf16 v[24:27], v[180:183], v[206:209], v[24:27]
	v_mfma_f32_16x16x32_bf16 v[16:19], v[172:175], v[214:217], v[16:19]
	v_mfma_f32_16x16x32_bf16 v[8:11], v[180:183], v[214:217], v[8:11]
	v_mfma_f32_16x16x32_bf16 v[4:7], v[172:175], v[222:225], v[4:7]
	v_mfma_f32_16x16x32_bf16 v[0:3], v[180:183], v[222:225], v[0:3]
	v_mfma_f32_16x16x32_bf16 v[48:51], v[176:179], v[202:205], v[48:51]
	v_mfma_f32_16x16x32_bf16 v[40:43], v[184:187], v[202:205], v[40:43]
	v_mfma_f32_16x16x32_bf16 v[32:35], v[176:179], v[210:213], v[32:35]
	v_mfma_f32_16x16x32_bf16 v[24:27], v[184:187], v[210:213], v[24:27]
	v_mfma_f32_16x16x32_bf16 v[16:19], v[176:179], v[218:221], v[16:19]
	v_mfma_f32_16x16x32_bf16 v[8:11], v[184:187], v[218:221], v[8:11]
	v_mfma_f32_16x16x32_bf16 v[4:7], v[176:179], v[226:229], v[4:7]
	v_mfma_f32_16x16x32_bf16 v[0:3], v[184:187], v[226:229], v[0:3]
	s_setprio 0
	s_barrier
	s_add_i32 s16, 0, 0x18000
	s_add_i32 s17, 0, 0x1c000
	v_add_u32_e32 v168, s16, v142
	v_add_u32_e32 v184, s17, v142
	ds_read_b128 v[156:159], v168
	ds_read_b128 v[160:163], v168 offset:1024
	ds_read_b128 v[164:167], v168 offset:2048
	ds_read_b128 v[168:171], v168 offset:3072
	ds_read_b128 v[172:175], v184
	ds_read_b128 v[176:179], v184 offset:1024
	ds_read_b128 v[180:183], v184 offset:2048
	ds_read_b128 v[184:187], v184 offset:3072
	s_add_u32 s8, s18, 0x40000
	s_addc_u32 s9, s19, 0
	s_mov_b32 m0, s65
	v_lshl_add_u64 v[234:235], s[8:9], 0, v[132:133]
	ds_read_b128 v[188:191], v143 offset:32768
	ds_read_b128 v[202:205], v143 offset:33792
	ds_read_b128 v[206:209], v143 offset:34816
	ds_read_b128 v[210:213], v143 offset:35840
	ds_read_b128 v[214:217], v143 offset:36864
	ds_read_b128 v[218:221], v143 offset:37888
	ds_read_b128 v[222:225], v143 offset:38912
	ds_read_b128 v[226:229], v143 offset:39936
	global_load_lds_dwordx4 v[234:235], off
	v_lshl_add_u64 v[234:235], s[8:9], 0, v[130:131]
	s_mov_b32 m0, s68
	s_nop 0
	global_load_lds_dwordx4 v[234:235], off
	s_waitcnt vmcnt(8)
	s_waitcnt lgkmcnt(0)
	s_barrier
	s_setprio 1
	s_waitcnt lgkmcnt(0)
	v_mfma_f32_16x16x32_bf16 v[124:127], v[156:159], v[188:191], v[124:127]
	v_mfma_f32_16x16x32_bf16 v[120:123], v[164:167], v[188:191], v[120:123]
	v_mfma_f32_16x16x32_bf16 v[108:111], v[156:159], v[206:209], v[108:111]
	v_mfma_f32_16x16x32_bf16 v[104:107], v[164:167], v[206:209], v[104:107]
	v_mfma_f32_16x16x32_bf16 v[100:103], v[156:159], v[214:217], v[100:103]
	v_mfma_f32_16x16x32_bf16 v[92:95], v[164:167], v[214:217], v[92:95]
	v_mfma_f32_16x16x32_bf16 v[84:87], v[156:159], v[222:225], v[84:87]
	v_mfma_f32_16x16x32_bf16 v[76:79], v[164:167], v[222:225], v[76:79]
	v_mfma_f32_16x16x32_bf16 v[124:127], v[160:163], v[202:205], v[124:127]
	v_mfma_f32_16x16x32_bf16 v[120:123], v[168:171], v[202:205], v[120:123]
	v_mfma_f32_16x16x32_bf16 v[108:111], v[160:163], v[210:213], v[108:111]
	v_mfma_f32_16x16x32_bf16 v[104:107], v[168:171], v[210:213], v[104:107]
	v_mfma_f32_16x16x32_bf16 v[100:103], v[160:163], v[218:221], v[100:103]
	v_mfma_f32_16x16x32_bf16 v[92:95], v[168:171], v[218:221], v[92:95]
	v_mfma_f32_16x16x32_bf16 v[84:87], v[160:163], v[226:229], v[84:87]
	v_mfma_f32_16x16x32_bf16 v[76:79], v[168:171], v[226:229], v[76:79]
	s_setprio 0
	s_setprio 1
	v_mfma_f32_16x16x32_bf16 v[116:119], v[172:175], v[188:191], v[116:119]
	v_mfma_f32_16x16x32_bf16 v[112:115], v[180:183], v[188:191], v[112:115]
	v_mfma_f32_16x16x32_bf16 v[96:99], v[172:175], v[206:209], v[96:99]
	v_mfma_f32_16x16x32_bf16 v[88:91], v[180:183], v[206:209], v[88:91]
	v_mfma_f32_16x16x32_bf16 v[80:83], v[172:175], v[214:217], v[80:83]
	v_mfma_f32_16x16x32_bf16 v[72:75], v[180:183], v[214:217], v[72:75]
	v_mfma_f32_16x16x32_bf16 v[68:71], v[172:175], v[222:225], v[68:71]
	v_mfma_f32_16x16x32_bf16 v[64:67], v[180:183], v[222:225], v[64:67]
	v_mfma_f32_16x16x32_bf16 v[116:119], v[176:179], v[202:205], v[116:119]
	v_mfma_f32_16x16x32_bf16 v[112:115], v[184:187], v[202:205], v[112:115]
	v_mfma_f32_16x16x32_bf16 v[96:99], v[176:179], v[210:213], v[96:99]
	v_mfma_f32_16x16x32_bf16 v[88:91], v[184:187], v[210:213], v[88:91]
	v_mfma_f32_16x16x32_bf16 v[80:83], v[176:179], v[218:221], v[80:83]
	v_mfma_f32_16x16x32_bf16 v[72:75], v[184:187], v[218:221], v[72:75]
	v_mfma_f32_16x16x32_bf16 v[68:71], v[176:179], v[226:229], v[68:71]
	v_mfma_f32_16x16x32_bf16 v[64:67], v[184:187], v[226:229], v[64:67]
	s_setprio 0
	s_barrier
	s_add_i32 s8, s16, s50
	v_lshl_add_u64 v[146:147], v[146:147], 0, s[70:71]
	s_mov_b32 m0, s8
	ds_read_b128 v[188:191], v143 offset:49152
	ds_read_b128 v[202:205], v143 offset:50176
	ds_read_b128 v[206:209], v143 offset:51200
	ds_read_b128 v[210:213], v143 offset:52224
	ds_read_b128 v[214:217], v143 offset:53248
	ds_read_b128 v[218:221], v143 offset:54272
	ds_read_b128 v[222:225], v143 offset:55296
	ds_read_b128 v[226:229], v143 offset:56320
	global_load_lds_dwordx4 v[146:147], off
	s_add_i32 m0, s8, 0x2000
	s_add_u32 s6, s6, 0x40080
	v_lshl_add_u64 v[146:147], v[154:155], 0, s[70:71]
	s_addc_u32 s7, s7, 0
	s_add_i32 s8, s17, s50
	global_load_lds_dwordx4 v[146:147], off
	v_lshl_add_u64 v[146:147], s[6:7], 0, v[144:145]
	s_mov_b32 m0, s8
	s_nop 0
	global_load_lds_dwordx4 v[146:147], off
	v_lshl_add_u64 v[146:147], s[6:7], 0, v[128:129]
	s_add_i32 m0, s8, 0x2000
	s_nop 0
	global_load_lds_dwordx4 v[146:147], off
	v_lshl_add_u64 v[146:147], v[230:231], 0, s[70:71]
	s_mov_b32 m0, s69
	s_nop 0
	global_load_lds_dwordx4 v[146:147], off
	v_lshl_add_u64 v[146:147], v[232:233], 0, s[70:71]
	s_mov_b32 m0, s84
	s_nop 0
	global_load_lds_dwordx4 v[146:147], off
	s_waitcnt vmcnt(8)
	s_waitcnt lgkmcnt(0)
	s_barrier
	s_setprio 1
	s_waitcnt lgkmcnt(0)
	v_mfma_f32_16x16x32_bf16 v[60:63], v[156:159], v[188:191], v[60:63]
	v_mfma_f32_16x16x32_bf16 v[56:59], v[164:167], v[188:191], v[56:59]
	v_mfma_f32_16x16x32_bf16 v[52:55], v[156:159], v[206:209], v[52:55]
	v_mfma_f32_16x16x32_bf16 v[44:47], v[164:167], v[206:209], v[44:47]
	v_mfma_f32_16x16x32_bf16 v[36:39], v[156:159], v[214:217], v[36:39]
	v_mfma_f32_16x16x32_bf16 v[28:31], v[164:167], v[214:217], v[28:31]
	v_mfma_f32_16x16x32_bf16 v[20:23], v[156:159], v[222:225], v[20:23]
	v_mfma_f32_16x16x32_bf16 v[12:15], v[164:167], v[222:225], v[12:15]
	v_mfma_f32_16x16x32_bf16 v[60:63], v[160:163], v[202:205], v[60:63]
	v_mfma_f32_16x16x32_bf16 v[56:59], v[168:171], v[202:205], v[56:59]
	v_mfma_f32_16x16x32_bf16 v[52:55], v[160:163], v[210:213], v[52:55]
	v_mfma_f32_16x16x32_bf16 v[44:47], v[168:171], v[210:213], v[44:47]
	v_mfma_f32_16x16x32_bf16 v[36:39], v[160:163], v[218:221], v[36:39]
	v_mfma_f32_16x16x32_bf16 v[28:31], v[168:171], v[218:221], v[28:31]
	v_mfma_f32_16x16x32_bf16 v[20:23], v[160:163], v[226:229], v[20:23]
	v_mfma_f32_16x16x32_bf16 v[12:15], v[168:171], v[226:229], v[12:15]
	s_setprio 0
	s_setprio 1
	v_mfma_f32_16x16x32_bf16 v[48:51], v[172:175], v[188:191], v[48:51]
	s_add_i32 s15, s15, 2
	s_add_u32 s40, s40, 0x100
	s_addc_u32 s41, s41, 0
	s_cmp_gt_u32 s15, 13
	v_mfma_f32_16x16x32_bf16 v[40:43], v[180:183], v[188:191], v[40:43]
	v_mfma_f32_16x16x32_bf16 v[32:35], v[172:175], v[206:209], v[32:35]
	v_mfma_f32_16x16x32_bf16 v[24:27], v[180:183], v[206:209], v[24:27]
	v_mfma_f32_16x16x32_bf16 v[16:19], v[172:175], v[214:217], v[16:19]
	v_mfma_f32_16x16x32_bf16 v[8:11], v[180:183], v[214:217], v[8:11]
	v_mfma_f32_16x16x32_bf16 v[4:7], v[172:175], v[222:225], v[4:7]
	v_mfma_f32_16x16x32_bf16 v[0:3], v[180:183], v[222:225], v[0:3]
	v_mfma_f32_16x16x32_bf16 v[48:51], v[176:179], v[202:205], v[48:51]
	v_mfma_f32_16x16x32_bf16 v[40:43], v[184:187], v[202:205], v[40:43]
	v_mfma_f32_16x16x32_bf16 v[32:35], v[176:179], v[210:213], v[32:35]
	v_mfma_f32_16x16x32_bf16 v[24:27], v[184:187], v[210:213], v[24:27]
	v_mfma_f32_16x16x32_bf16 v[16:19], v[176:179], v[218:221], v[16:19]
	v_mfma_f32_16x16x32_bf16 v[8:11], v[184:187], v[218:221], v[8:11]
	v_mfma_f32_16x16x32_bf16 v[4:7], v[176:179], v[226:229], v[4:7]
	v_mfma_f32_16x16x32_bf16 v[0:3], v[184:187], v[226:229], v[0:3]
	s_setprio 0
	s_barrier
	s_cbranch_scc0 .LBB0_741
	s_add_u32 s6, s13, 0xffffff00
	s_addc_u32 s7, s14, -1
	s_and_b64 vcc, exec, s[38:39]
	s_cbranch_vccnz .LBB0_730
	v_mov_b32_e32 v0, 0
	s_mov_b32 s25, s4
	s_mov_b32 s24, s12
	s_mov_b64 s[2:3], s[44:45]
	s_mov_b32 s85, s10
	v_mov_b32_e32 v1, v0
	v_mov_b32_e32 v2, v0
	v_mov_b32_e32 v3, v0
	v_mov_b32_e32 v4, v0
	v_mov_b32_e32 v5, v0
	v_mov_b32_e32 v6, v0
	v_mov_b32_e32 v7, v0
	v_mov_b32_e32 v8, v0
	v_mov_b32_e32 v9, v0
	v_mov_b32_e32 v10, v0
	v_mov_b32_e32 v11, v0
	v_mov_b32_e32 v16, v0
	v_mov_b32_e32 v17, v0
	v_mov_b32_e32 v18, v0
	v_mov_b32_e32 v19, v0
	v_mov_b32_e32 v24, v0
	v_mov_b32_e32 v25, v0
	v_mov_b32_e32 v26, v0
	v_mov_b32_e32 v27, v0
	v_mov_b32_e32 v32, v0
	v_mov_b32_e32 v33, v0
	v_mov_b32_e32 v34, v0
	v_mov_b32_e32 v35, v0
	v_mov_b32_e32 v40, v0
	v_mov_b32_e32 v41, v0
	v_mov_b32_e32 v42, v0
	v_mov_b32_e32 v43, v0
	v_mov_b32_e32 v48, v0
	v_mov_b32_e32 v49, v0
	v_mov_b32_e32 v50, v0
	v_mov_b32_e32 v51, v0
	v_mov_b32_e32 v12, v0
	v_mov_b32_e32 v13, v0
	v_mov_b32_e32 v14, v0
	v_mov_b32_e32 v15, v0
	v_mov_b32_e32 v20, v0
	v_mov_b32_e32 v21, v0
	v_mov_b32_e32 v22, v0
	v_mov_b32_e32 v23, v0
	v_mov_b32_e32 v28, v0
	v_mov_b32_e32 v29, v0
	v_mov_b32_e32 v30, v0
	v_mov_b32_e32 v31, v0
	v_mov_b32_e32 v36, v0
	v_mov_b32_e32 v37, v0
	v_mov_b32_e32 v38, v0
	v_mov_b32_e32 v39, v0
	v_mov_b32_e32 v44, v0
	v_mov_b32_e32 v45, v0
	v_mov_b32_e32 v46, v0
	v_mov_b32_e32 v47, v0
	v_mov_b32_e32 v52, v0
	v_mov_b32_e32 v53, v0
	v_mov_b32_e32 v54, v0
	v_mov_b32_e32 v55, v0
	v_mov_b32_e32 v56, v0
	v_mov_b32_e32 v57, v0
	v_mov_b32_e32 v58, v0
	v_mov_b32_e32 v59, v0
	v_mov_b32_e32 v60, v0
	v_mov_b32_e32 v61, v0
	v_mov_b32_e32 v62, v0
	v_mov_b32_e32 v63, v0
	v_mov_b32_e32 v64, v0
	v_mov_b32_e32 v65, v0
	v_mov_b32_e32 v66, v0
	v_mov_b32_e32 v67, v0
	v_mov_b32_e32 v68, v0
	v_mov_b32_e32 v69, v0
	v_mov_b32_e32 v70, v0
	v_mov_b32_e32 v71, v0
	v_mov_b32_e32 v72, v0
	v_mov_b32_e32 v73, v0
	v_mov_b32_e32 v74, v0
	v_mov_b32_e32 v75, v0
	v_mov_b32_e32 v80, v0
	v_mov_b32_e32 v81, v0
	v_mov_b32_e32 v82, v0
	v_mov_b32_e32 v83, v0
	v_mov_b32_e32 v88, v0
	v_mov_b32_e32 v89, v0
	v_mov_b32_e32 v90, v0
	v_mov_b32_e32 v91, v0
	v_mov_b32_e32 v96, v0
	v_mov_b32_e32 v97, v0
	v_mov_b32_e32 v98, v0
	v_mov_b32_e32 v99, v0
	v_mov_b32_e32 v112, v0
	v_mov_b32_e32 v113, v0
	v_mov_b32_e32 v114, v0
	v_mov_b32_e32 v115, v0
	v_mov_b32_e32 v116, v0
	v_mov_b32_e32 v117, v0
	v_mov_b32_e32 v118, v0
	v_mov_b32_e32 v119, v0
	v_mov_b32_e32 v76, v0
	v_mov_b32_e32 v77, v0
	v_mov_b32_e32 v78, v0
	v_mov_b32_e32 v79, v0
	v_mov_b32_e32 v84, v0
	v_mov_b32_e32 v85, v0
	v_mov_b32_e32 v86, v0
	v_mov_b32_e32 v87, v0
	v_mov_b32_e32 v92, v0
	v_mov_b32_e32 v93, v0
	v_mov_b32_e32 v94, v0
	v_mov_b32_e32 v95, v0
	v_mov_b32_e32 v100, v0
	v_mov_b32_e32 v101, v0
	v_mov_b32_e32 v102, v0
	v_mov_b32_e32 v103, v0
	v_mov_b32_e32 v104, v0
	v_mov_b32_e32 v105, v0
	v_mov_b32_e32 v106, v0
	v_mov_b32_e32 v107, v0
	v_mov_b32_e32 v108, v0
	v_mov_b32_e32 v109, v0
	v_mov_b32_e32 v110, v0
	v_mov_b32_e32 v111, v0
	v_mov_b32_e32 v120, v0
	v_mov_b32_e32 v121, v0
	v_mov_b32_e32 v122, v0
	v_mov_b32_e32 v123, v0
	v_mov_b32_e32 v124, v0
	v_mov_b32_e32 v125, v0
	v_mov_b32_e32 v126, v0
	v_mov_b32_e32 v127, v0
	s_andn2_b64 vcc, exec, s[36:37]
	s_cbranch_vccnz .LBB0_731

.LBB0_993:
	s_add_i32 s8, 0, 0x10000
	v_add_u32_e32 v143, s8, v139
	s_add_i32 s27, 0, 0x14000
	ds_read_b128 v[156:159], v143
	ds_read_b128 v[160:163], v143 offset:1024
	ds_read_b128 v[164:167], v143 offset:2048
	ds_read_b128 v[168:171], v143 offset:3072
	v_add_u32_e32 v143, s27, v139
	ds_read_b128 v[172:175], v143
	ds_read_b128 v[176:179], v143 offset:1024
	ds_read_b128 v[180:183], v143 offset:2048
	ds_read_b128 v[184:187], v143 offset:3072
	s_add_u32 s6, s48, 0xfffc0080
	s_addc_u32 s7, s49, -1
	s_cmp_eq_u32 s31, 12
	s_cselect_b32 s19, s14, s7
	s_cselect_b32 s18, s15, s6
	s_cselect_b32 s7, s16, s30
	s_cselect_b32 s6, s17, s23
	v_lshl_add_u64 v[146:147], s[48:49], 0, v[134:135]
	s_add_i32 m0, s64, 0xc000
	ds_read_b128 v[188:191], v142
	ds_read_b128 v[198:201], v142 offset:1024
	ds_read_b128 v[202:205], v142 offset:2048
	ds_read_b128 v[206:209], v142 offset:3072
	ds_read_b128 v[210:213], v142 offset:4096
	ds_read_b128 v[214:217], v142 offset:5120
	ds_read_b128 v[218:221], v142 offset:6144
	ds_read_b128 v[222:225], v142 offset:7168
	global_load_lds_dwordx4 v[146:147], off
	v_lshl_add_u64 v[146:147], s[48:49], 0, v[136:137]
	s_add_i32 m0, s64, 0xe000
	s_nop 0
	global_load_lds_dwordx4 v[146:147], off
	s_waitcnt vmcnt(8)
	s_waitcnt lgkmcnt(0)
	s_barrier
	s_setprio 1
	s_waitcnt lgkmcnt(0)
	v_mfma_f32_16x16x32_bf16 v[124:127], v[156:159], v[188:191], v[124:127]
	v_mfma_f32_16x16x32_bf16 v[120:123], v[164:167], v[188:191], v[120:123]
	v_mfma_f32_16x16x32_bf16 v[108:111], v[156:159], v[202:205], v[108:111]
	v_mfma_f32_16x16x32_bf16 v[104:107], v[164:167], v[202:205], v[104:107]
	v_mfma_f32_16x16x32_bf16 v[92:95], v[156:159], v[210:213], v[92:95]
	v_mfma_f32_16x16x32_bf16 v[88:91], v[164:167], v[210:213], v[88:91]
	v_mfma_f32_16x16x32_bf16 v[76:79], v[156:159], v[218:221], v[76:79]
	v_mfma_f32_16x16x32_bf16 v[72:75], v[164:167], v[218:221], v[72:75]
	v_mfma_f32_16x16x32_bf16 v[124:127], v[160:163], v[198:201], v[124:127]
	v_mfma_f32_16x16x32_bf16 v[120:123], v[168:171], v[198:201], v[120:123]
	v_mfma_f32_16x16x32_bf16 v[108:111], v[160:163], v[206:209], v[108:111]
	v_mfma_f32_16x16x32_bf16 v[104:107], v[168:171], v[206:209], v[104:107]
	v_mfma_f32_16x16x32_bf16 v[92:95], v[160:163], v[214:217], v[92:95]
	v_mfma_f32_16x16x32_bf16 v[88:91], v[168:171], v[214:217], v[88:91]
	v_mfma_f32_16x16x32_bf16 v[76:79], v[160:163], v[222:225], v[76:79]
	v_mfma_f32_16x16x32_bf16 v[72:75], v[168:171], v[222:225], v[72:75]
	s_setprio 0
	s_setprio 1
	v_mfma_f32_16x16x32_bf16 v[116:119], v[172:175], v[188:191], v[116:119]
	v_mfma_f32_16x16x32_bf16 v[112:115], v[180:183], v[188:191], v[112:115]
	v_mfma_f32_16x16x32_bf16 v[100:103], v[172:175], v[202:205], v[100:103]
	v_mfma_f32_16x16x32_bf16 v[96:99], v[180:183], v[202:205], v[96:99]
	v_mfma_f32_16x16x32_bf16 v[84:87], v[172:175], v[210:213], v[84:87]
	v_mfma_f32_16x16x32_bf16 v[80:83], v[180:183], v[210:213], v[80:83]
	v_mfma_f32_16x16x32_bf16 v[68:71], v[172:175], v[218:221], v[68:71]
	v_mfma_f32_16x16x32_bf16 v[64:67], v[180:183], v[218:221], v[64:67]
	v_mfma_f32_16x16x32_bf16 v[116:119], v[176:179], v[198:201], v[116:119]
	v_mfma_f32_16x16x32_bf16 v[112:115], v[184:187], v[198:201], v[112:115]
	v_mfma_f32_16x16x32_bf16 v[100:103], v[176:179], v[206:209], v[100:103]
	v_mfma_f32_16x16x32_bf16 v[96:99], v[184:187], v[206:209], v[96:99]
	v_mfma_f32_16x16x32_bf16 v[84:87], v[176:179], v[214:217], v[84:87]
	v_mfma_f32_16x16x32_bf16 v[80:83], v[184:187], v[214:217], v[80:83]
	v_mfma_f32_16x16x32_bf16 v[68:71], v[176:179], v[222:225], v[68:71]
	v_mfma_f32_16x16x32_bf16 v[64:67], v[184:187], v[222:225], v[64:67]
	s_setprio 0
	s_barrier
	s_add_i32 s8, s8, s0
	v_lshl_add_u64 v[146:147], s[6:7], 0, v[144:145]
	s_mov_b32 m0, s8
	ds_read_b128 v[188:191], v142 offset:16384
	ds_read_b128 v[198:201], v142 offset:17408
	ds_read_b128 v[202:205], v142 offset:18432
	ds_read_b128 v[206:209], v142 offset:19456
	ds_read_b128 v[210:213], v142 offset:20480
	ds_read_b128 v[214:217], v142 offset:21504
	ds_read_b128 v[218:221], v142 offset:22528
	ds_read_b128 v[222:225], v142 offset:23552
	global_load_lds_dwordx4 v[146:147], off
	s_add_i32 m0, s8, 0x2000
	s_add_u32 s8, s6, 0x40000
	v_lshl_add_u64 v[154:155], s[6:7], 0, v[128:129]
	s_addc_u32 s9, s7, 0
	s_add_i32 s27, s27, s0
	global_load_lds_dwordx4 v[154:155], off
	v_lshl_add_u64 v[226:227], s[8:9], 0, v[144:145]
	s_mov_b32 m0, s27
	v_lshl_add_u64 v[228:229], s[18:19], 0, v[130:131]
	global_load_lds_dwordx4 v[226:227], off
	v_lshl_add_u64 v[226:227], s[8:9], 0, v[128:129]
	s_add_i32 m0, s27, 0x2000
	s_nop 0
	global_load_lds_dwordx4 v[226:227], off
	v_lshl_add_u64 v[226:227], s[18:19], 0, v[132:133]
	s_mov_b32 m0, s64
	s_nop 0
	global_load_lds_dwordx4 v[226:227], off
	s_mov_b32 m0, s65
	s_nop 0
	global_load_lds_dwordx4 v[228:229], off
	s_waitcnt vmcnt(8)
	s_waitcnt lgkmcnt(0)
	s_barrier
	s_setprio 1
	s_waitcnt lgkmcnt(0)
	v_mfma_f32_16x16x32_bf16 v[60:63], v[156:159], v[188:191], v[60:63]
	v_mfma_f32_16x16x32_bf16 v[56:59], v[164:167], v[188:191], v[56:59]
	v_mfma_f32_16x16x32_bf16 v[44:47], v[156:159], v[202:205], v[44:47]
	v_mfma_f32_16x16x32_bf16 v[40:43], v[164:167], v[202:205], v[40:43]
	v_mfma_f32_16x16x32_bf16 v[28:31], v[156:159], v[210:213], v[28:31]
	v_mfma_f32_16x16x32_bf16 v[24:27], v[164:167], v[210:213], v[24:27]
	v_mfma_f32_16x16x32_bf16 v[12:15], v[156:159], v[218:221], v[12:15]
	v_mfma_f32_16x16x32_bf16 v[8:11], v[164:167], v[218:221], v[8:11]
	v_mfma_f32_16x16x32_bf16 v[60:63], v[160:163], v[198:201], v[60:63]
	v_mfma_f32_16x16x32_bf16 v[56:59], v[168:171], v[198:201], v[56:59]
	v_mfma_f32_16x16x32_bf16 v[44:47], v[160:163], v[206:209], v[44:47]
	v_mfma_f32_16x16x32_bf16 v[40:43], v[168:171], v[206:209], v[40:43]
	v_mfma_f32_16x16x32_bf16 v[28:31], v[160:163], v[214:217], v[28:31]
	v_mfma_f32_16x16x32_bf16 v[24:27], v[168:171], v[214:217], v[24:27]
	v_mfma_f32_16x16x32_bf16 v[12:15], v[160:163], v[222:225], v[12:15]
	v_mfma_f32_16x16x32_bf16 v[8:11], v[168:171], v[222:225], v[8:11]
	s_setprio 0
	s_setprio 1
	v_mfma_f32_16x16x32_bf16 v[52:55], v[172:175], v[188:191], v[52:55]
	v_mfma_f32_16x16x32_bf16 v[48:51], v[180:183], v[188:191], v[48:51]
	v_mfma_f32_16x16x32_bf16 v[36:39], v[172:175], v[202:205], v[36:39]
	v_mfma_f32_16x16x32_bf16 v[32:35], v[180:183], v[202:205], v[32:35]
	v_mfma_f32_16x16x32_bf16 v[20:23], v[172:175], v[210:213], v[20:23]
	v_mfma_f32_16x16x32_bf16 v[16:19], v[180:183], v[210:213], v[16:19]
	v_mfma_f32_16x16x32_bf16 v[4:7], v[172:175], v[218:221], v[4:7]
	v_mfma_f32_16x16x32_bf16 v[0:3], v[180:183], v[218:221], v[0:3]
	v_mfma_f32_16x16x32_bf16 v[52:55], v[176:179], v[198:201], v[52:55]
	v_mfma_f32_16x16x32_bf16 v[48:51], v[184:187], v[198:201], v[48:51]
	v_mfma_f32_16x16x32_bf16 v[36:39], v[176:179], v[206:209], v[36:39]
	v_mfma_f32_16x16x32_bf16 v[32:35], v[184:187], v[206:209], v[32:35]
	v_mfma_f32_16x16x32_bf16 v[20:23], v[176:179], v[214:217], v[20:23]
	v_mfma_f32_16x16x32_bf16 v[16:19], v[184:187], v[214:217], v[16:19]
	v_mfma_f32_16x16x32_bf16 v[4:7], v[176:179], v[222:225], v[4:7]
	v_mfma_f32_16x16x32_bf16 v[0:3], v[184:187], v[222:225], v[0:3]
	s_setprio 0
	s_barrier
	s_add_i32 s27, 0, 0x18000
	v_add_u32_e32 v143, s27, v139
	s_add_i32 s33, 0, 0x1c000
	ds_read_b128 v[156:159], v143
	ds_read_b128 v[160:163], v143 offset:1024
	ds_read_b128 v[164:167], v143 offset:2048
	ds_read_b128 v[168:171], v143 offset:3072
	v_add_u32_e32 v143, s33, v139
	ds_read_b128 v[172:175], v143
	ds_read_b128 v[176:179], v143 offset:1024
	ds_read_b128 v[180:183], v143 offset:2048
	ds_read_b128 v[184:187], v143 offset:3072
	s_add_u32 s8, s18, 0x40000
	s_addc_u32 s9, s19, 0
	s_mov_b32 m0, s68
	v_lshl_add_u64 v[230:231], s[8:9], 0, v[132:133]
	ds_read_b128 v[188:191], v142 offset:32768
	ds_read_b128 v[198:201], v142 offset:33792
	ds_read_b128 v[202:205], v142 offset:34816
	ds_read_b128 v[206:209], v142 offset:35840
	ds_read_b128 v[210:213], v142 offset:36864
	ds_read_b128 v[214:217], v142 offset:37888
	ds_read_b128 v[218:221], v142 offset:38912
	ds_read_b128 v[222:225], v142 offset:39936
	global_load_lds_dwordx4 v[230:231], off
	v_lshl_add_u64 v[230:231], s[8:9], 0, v[130:131]
	s_mov_b32 m0, s69
	s_nop 0
	global_load_lds_dwordx4 v[230:231], off
	s_waitcnt vmcnt(8)
	s_waitcnt lgkmcnt(0)
	s_barrier
	s_setprio 1
	s_waitcnt lgkmcnt(0)
	v_mfma_f32_16x16x32_bf16 v[124:127], v[156:159], v[188:191], v[124:127]
	v_mfma_f32_16x16x32_bf16 v[120:123], v[164:167], v[188:191], v[120:123]
	v_mfma_f32_16x16x32_bf16 v[108:111], v[156:159], v[202:205], v[108:111]
	v_mfma_f32_16x16x32_bf16 v[104:107], v[164:167], v[202:205], v[104:107]
	v_mfma_f32_16x16x32_bf16 v[92:95], v[156:159], v[210:213], v[92:95]
	v_mfma_f32_16x16x32_bf16 v[88:91], v[164:167], v[210:213], v[88:91]
	v_mfma_f32_16x16x32_bf16 v[76:79], v[156:159], v[218:221], v[76:79]
	v_mfma_f32_16x16x32_bf16 v[72:75], v[164:167], v[218:221], v[72:75]
	v_mfma_f32_16x16x32_bf16 v[124:127], v[160:163], v[198:201], v[124:127]
	v_mfma_f32_16x16x32_bf16 v[120:123], v[168:171], v[198:201], v[120:123]
	v_mfma_f32_16x16x32_bf16 v[108:111], v[160:163], v[206:209], v[108:111]
	v_mfma_f32_16x16x32_bf16 v[104:107], v[168:171], v[206:209], v[104:107]
	v_mfma_f32_16x16x32_bf16 v[92:95], v[160:163], v[214:217], v[92:95]
	v_mfma_f32_16x16x32_bf16 v[88:91], v[168:171], v[214:217], v[88:91]
	v_mfma_f32_16x16x32_bf16 v[76:79], v[160:163], v[222:225], v[76:79]
	v_mfma_f32_16x16x32_bf16 v[72:75], v[168:171], v[222:225], v[72:75]
	s_setprio 0
	s_setprio 1
	v_mfma_f32_16x16x32_bf16 v[116:119], v[172:175], v[188:191], v[116:119]
	v_mfma_f32_16x16x32_bf16 v[112:115], v[180:183], v[188:191], v[112:115]
	v_mfma_f32_16x16x32_bf16 v[100:103], v[172:175], v[202:205], v[100:103]
	v_mfma_f32_16x16x32_bf16 v[96:99], v[180:183], v[202:205], v[96:99]
	v_mfma_f32_16x16x32_bf16 v[84:87], v[172:175], v[210:213], v[84:87]
	v_mfma_f32_16x16x32_bf16 v[80:83], v[180:183], v[210:213], v[80:83]
	v_mfma_f32_16x16x32_bf16 v[68:71], v[172:175], v[218:221], v[68:71]
	v_mfma_f32_16x16x32_bf16 v[64:67], v[180:183], v[218:221], v[64:67]
	v_mfma_f32_16x16x32_bf16 v[116:119], v[176:179], v[198:201], v[116:119]
	v_mfma_f32_16x16x32_bf16 v[112:115], v[184:187], v[198:201], v[112:115]
	v_mfma_f32_16x16x32_bf16 v[100:103], v[176:179], v[206:209], v[100:103]
	v_mfma_f32_16x16x32_bf16 v[96:99], v[184:187], v[206:209], v[96:99]
	v_mfma_f32_16x16x32_bf16 v[84:87], v[176:179], v[214:217], v[84:87]
	v_mfma_f32_16x16x32_bf16 v[80:83], v[184:187], v[214:217], v[80:83]
	v_mfma_f32_16x16x32_bf16 v[68:71], v[176:179], v[222:225], v[68:71]
	v_mfma_f32_16x16x32_bf16 v[64:67], v[184:187], v[222:225], v[64:67]
	s_setprio 0
	s_barrier
	s_add_i32 s8, s27, s0
	v_lshl_add_u64 v[146:147], v[146:147], 0, s[70:71]
	s_mov_b32 m0, s8
	ds_read_b128 v[188:191], v142 offset:49152
	ds_read_b128 v[198:201], v142 offset:50176
	ds_read_b128 v[202:205], v142 offset:51200
	ds_read_b128 v[206:209], v142 offset:52224
	ds_read_b128 v[210:213], v142 offset:53248
	ds_read_b128 v[214:217], v142 offset:54272
	ds_read_b128 v[218:221], v142 offset:55296
	ds_read_b128 v[222:225], v142 offset:56320
	global_load_lds_dwordx4 v[146:147], off
	s_add_i32 m0, s8, 0x2000
	s_add_u32 s6, s6, 0x40080
	v_lshl_add_u64 v[146:147], v[154:155], 0, s[70:71]
	s_addc_u32 s7, s7, 0
	s_add_i32 s8, s33, s0
	global_load_lds_dwordx4 v[146:147], off
	v_lshl_add_u64 v[146:147], s[6:7], 0, v[144:145]
	s_mov_b32 m0, s8
	s_nop 0
	global_load_lds_dwordx4 v[146:147], off
	v_lshl_add_u64 v[146:147], s[6:7], 0, v[128:129]
	s_add_i32 m0, s8, 0x2000
	s_nop 0
	global_load_lds_dwordx4 v[146:147], off
	v_lshl_add_u64 v[146:147], v[226:227], 0, s[70:71]
	s_mov_b32 m0, s84
	s_nop 0
	global_load_lds_dwordx4 v[146:147], off
	v_lshl_add_u64 v[146:147], v[228:229], 0, s[70:71]
	s_mov_b32 m0, s85
	s_nop 0
	global_load_lds_dwordx4 v[146:147], off
	s_waitcnt vmcnt(8)
	s_waitcnt lgkmcnt(0)
	s_barrier
	s_setprio 1
	s_waitcnt lgkmcnt(0)
	v_mfma_f32_16x16x32_bf16 v[60:63], v[156:159], v[188:191], v[60:63]
	v_mfma_f32_16x16x32_bf16 v[56:59], v[164:167], v[188:191], v[56:59]
	v_mfma_f32_16x16x32_bf16 v[44:47], v[156:159], v[202:205], v[44:47]
	v_mfma_f32_16x16x32_bf16 v[40:43], v[164:167], v[202:205], v[40:43]
	v_mfma_f32_16x16x32_bf16 v[28:31], v[156:159], v[210:213], v[28:31]
	v_mfma_f32_16x16x32_bf16 v[24:27], v[164:167], v[210:213], v[24:27]
	v_mfma_f32_16x16x32_bf16 v[12:15], v[156:159], v[218:221], v[12:15]
	v_mfma_f32_16x16x32_bf16 v[8:11], v[164:167], v[218:221], v[8:11]
	v_mfma_f32_16x16x32_bf16 v[60:63], v[160:163], v[198:201], v[60:63]
	v_mfma_f32_16x16x32_bf16 v[56:59], v[168:171], v[198:201], v[56:59]
	v_mfma_f32_16x16x32_bf16 v[44:47], v[160:163], v[206:209], v[44:47]
	v_mfma_f32_16x16x32_bf16 v[40:43], v[168:171], v[206:209], v[40:43]
	v_mfma_f32_16x16x32_bf16 v[28:31], v[160:163], v[214:217], v[28:31]
	v_mfma_f32_16x16x32_bf16 v[24:27], v[168:171], v[214:217], v[24:27]
	v_mfma_f32_16x16x32_bf16 v[12:15], v[160:163], v[222:225], v[12:15]
	v_mfma_f32_16x16x32_bf16 v[8:11], v[168:171], v[222:225], v[8:11]
	s_setprio 0
	s_setprio 1
	v_mfma_f32_16x16x32_bf16 v[52:55], v[172:175], v[188:191], v[52:55]
	s_add_i32 s31, s31, 2
	s_add_u32 s48, s48, 0x100
	s_addc_u32 s49, s49, 0
	s_add_u32 s23, s23, 0x100
	s_addc_u32 s30, s30, 0
	s_cmp_gt_u32 s31, 13
	v_mfma_f32_16x16x32_bf16 v[48:51], v[180:183], v[188:191], v[48:51]
	v_mfma_f32_16x16x32_bf16 v[36:39], v[172:175], v[202:205], v[36:39]
	v_mfma_f32_16x16x32_bf16 v[32:35], v[180:183], v[202:205], v[32:35]
	v_mfma_f32_16x16x32_bf16 v[20:23], v[172:175], v[210:213], v[20:23]
	v_mfma_f32_16x16x32_bf16 v[16:19], v[180:183], v[210:213], v[16:19]
	v_mfma_f32_16x16x32_bf16 v[4:7], v[172:175], v[218:221], v[4:7]
	v_mfma_f32_16x16x32_bf16 v[0:3], v[180:183], v[218:221], v[0:3]
	v_mfma_f32_16x16x32_bf16 v[52:55], v[176:179], v[198:201], v[52:55]
	v_mfma_f32_16x16x32_bf16 v[48:51], v[184:187], v[198:201], v[48:51]
	v_mfma_f32_16x16x32_bf16 v[36:39], v[176:179], v[206:209], v[36:39]
	v_mfma_f32_16x16x32_bf16 v[32:35], v[184:187], v[206:209], v[32:35]
	v_mfma_f32_16x16x32_bf16 v[20:23], v[176:179], v[214:217], v[20:23]
	v_mfma_f32_16x16x32_bf16 v[16:19], v[184:187], v[214:217], v[16:19]
	v_mfma_f32_16x16x32_bf16 v[4:7], v[176:179], v[222:225], v[4:7]
	v_mfma_f32_16x16x32_bf16 v[0:3], v[184:187], v[222:225], v[0:3]
	s_setprio 0
	s_barrier
	s_cbranch_scc0 .LBB0_993
	s_and_b64 vcc, exec, s[38:39]
	s_cbranch_vccz .LBB0_996
	s_barrier

.LBB0_1018:
	s_add_i32 s27, 0, 0x10000
	v_add_u32_e32 v142, s27, v139
	s_add_i32 s52, 0, 0x14000
	ds_read_b128 v[156:159], v142
	ds_read_b128 v[160:163], v142 offset:1024
	ds_read_b128 v[164:167], v142 offset:2048
	ds_read_b128 v[168:171], v142 offset:3072
	v_add_u32_e32 v142, s52, v139
	ds_read_b128 v[172:175], v142
	ds_read_b128 v[176:179], v142 offset:1024
	ds_read_b128 v[180:183], v142 offset:2048
	ds_read_b128 v[184:187], v142 offset:3072
	s_add_u32 s8, s48, 0xfffc0080
	s_addc_u32 s9, s49, -1
	s_cmp_eq_u32 s51, 12
	s_cselect_b32 s19, s31, s9
	s_cselect_b32 s18, s33, s8
	s_cselect_b32 s25, s37, s50
	s_cselect_b32 s24, s41, s43
	v_lshl_add_u64 v[142:143], s[48:49], 0, v[134:135]
	s_add_i32 m0, s17, 0xc000
	ds_read_b128 v[188:191], v141
	ds_read_b128 v[198:201], v141 offset:1024
	ds_read_b128 v[202:205], v141 offset:2048
	ds_read_b128 v[206:209], v141 offset:3072
	ds_read_b128 v[210:213], v141 offset:4096
	ds_read_b128 v[214:217], v141 offset:5120
	ds_read_b128 v[218:221], v141 offset:6144
	ds_read_b128 v[222:225], v141 offset:7168
	global_load_lds_dwordx4 v[142:143], off
	v_lshl_add_u64 v[142:143], s[48:49], 0, v[136:137]
	s_add_i32 m0, s17, 0xe000
	s_nop 0
	global_load_lds_dwordx4 v[142:143], off
	s_waitcnt vmcnt(8)
	s_waitcnt lgkmcnt(0)
	s_barrier
	s_setprio 1
	s_waitcnt lgkmcnt(0)
	v_mfma_f32_16x16x32_bf16 v[124:127], v[156:159], v[188:191], v[124:127]
	v_mfma_f32_16x16x32_bf16 v[120:123], v[164:167], v[188:191], v[120:123]
	v_mfma_f32_16x16x32_bf16 v[116:119], v[156:159], v[202:205], v[116:119]
	v_mfma_f32_16x16x32_bf16 v[112:115], v[164:167], v[202:205], v[112:115]
	v_mfma_f32_16x16x32_bf16 v[100:103], v[156:159], v[210:213], v[100:103]
	v_mfma_f32_16x16x32_bf16 v[96:99], v[164:167], v[210:213], v[96:99]
	v_mfma_f32_16x16x32_bf16 v[84:87], v[156:159], v[218:221], v[84:87]
	v_mfma_f32_16x16x32_bf16 v[80:83], v[164:167], v[218:221], v[80:83]
	v_mfma_f32_16x16x32_bf16 v[124:127], v[160:163], v[198:201], v[124:127]
	v_mfma_f32_16x16x32_bf16 v[120:123], v[168:171], v[198:201], v[120:123]
	v_mfma_f32_16x16x32_bf16 v[116:119], v[160:163], v[206:209], v[116:119]
	v_mfma_f32_16x16x32_bf16 v[112:115], v[168:171], v[206:209], v[112:115]
	v_mfma_f32_16x16x32_bf16 v[100:103], v[160:163], v[214:217], v[100:103]
	v_mfma_f32_16x16x32_bf16 v[96:99], v[168:171], v[214:217], v[96:99]
	v_mfma_f32_16x16x32_bf16 v[84:87], v[160:163], v[222:225], v[84:87]
	v_mfma_f32_16x16x32_bf16 v[80:83], v[168:171], v[222:225], v[80:83]
	s_setprio 0
	s_setprio 1
	v_mfma_f32_16x16x32_bf16 v[108:111], v[172:175], v[188:191], v[108:111]
	v_mfma_f32_16x16x32_bf16 v[104:107], v[180:183], v[188:191], v[104:107]
	v_mfma_f32_16x16x32_bf16 v[92:95], v[172:175], v[202:205], v[92:95]
	v_mfma_f32_16x16x32_bf16 v[88:91], v[180:183], v[202:205], v[88:91]
	v_mfma_f32_16x16x32_bf16 v[76:79], v[172:175], v[210:213], v[76:79]
	v_mfma_f32_16x16x32_bf16 v[72:75], v[180:183], v[210:213], v[72:75]
	v_mfma_f32_16x16x32_bf16 v[68:71], v[172:175], v[218:221], v[68:71]
	v_mfma_f32_16x16x32_bf16 v[64:67], v[180:183], v[218:221], v[64:67]
	v_mfma_f32_16x16x32_bf16 v[108:111], v[176:179], v[198:201], v[108:111]
	v_mfma_f32_16x16x32_bf16 v[104:107], v[184:187], v[198:201], v[104:107]
	v_mfma_f32_16x16x32_bf16 v[92:95], v[176:179], v[206:209], v[92:95]
	v_mfma_f32_16x16x32_bf16 v[88:91], v[184:187], v[206:209], v[88:91]
	v_mfma_f32_16x16x32_bf16 v[76:79], v[176:179], v[214:217], v[76:79]
	v_mfma_f32_16x16x32_bf16 v[72:75], v[184:187], v[214:217], v[72:75]
	v_mfma_f32_16x16x32_bf16 v[68:71], v[176:179], v[222:225], v[68:71]
	v_mfma_f32_16x16x32_bf16 v[64:67], v[184:187], v[222:225], v[64:67]
	s_setprio 0
	s_barrier
	s_add_i32 s8, s27, s16
	v_lshl_add_u64 v[142:143], s[24:25], 0, v[144:145]
	s_mov_b32 m0, s8
	ds_read_b128 v[188:191], v141 offset:16384
	ds_read_b128 v[198:201], v141 offset:17408
	ds_read_b128 v[202:205], v141 offset:18432
	ds_read_b128 v[206:209], v141 offset:19456
	ds_read_b128 v[210:213], v141 offset:20480
	ds_read_b128 v[214:217], v141 offset:21504
	ds_read_b128 v[218:221], v141 offset:22528
	ds_read_b128 v[222:225], v141 offset:23552
	global_load_lds_dwordx4 v[142:143], off
	s_add_i32 m0, s8, 0x2000
	s_add_u32 s8, s24, 0x40000
	v_lshl_add_u64 v[146:147], s[24:25], 0, v[132:133]
	s_addc_u32 s9, s25, 0
	s_add_i32 s27, s52, s16
	global_load_lds_dwordx4 v[146:147], off
	v_lshl_add_u64 v[154:155], s[8:9], 0, v[144:145]
	s_mov_b32 m0, s27
	v_lshl_add_u64 v[226:227], s[18:19], 0, v[130:131]
	global_load_lds_dwordx4 v[154:155], off
	v_lshl_add_u64 v[154:155], s[8:9], 0, v[132:133]
	s_add_i32 m0, s27, 0x2000
	s_nop 0
	global_load_lds_dwordx4 v[154:155], off
	v_lshl_add_u64 v[154:155], s[18:19], 0, v[128:129]
	s_mov_b32 m0, s17
	s_nop 0
	global_load_lds_dwordx4 v[154:155], off
	s_mov_b32 m0, s14
	s_nop 0
	global_load_lds_dwordx4 v[226:227], off
	s_waitcnt vmcnt(8)
	s_waitcnt lgkmcnt(0)
	s_barrier
	s_setprio 1
	s_waitcnt lgkmcnt(0)
	v_mfma_f32_16x16x32_bf16 v[60:63], v[156:159], v[188:191], v[60:63]
	v_mfma_f32_16x16x32_bf16 v[56:59], v[164:167], v[188:191], v[56:59]
	v_mfma_f32_16x16x32_bf16 v[52:55], v[156:159], v[202:205], v[52:55]
	v_mfma_f32_16x16x32_bf16 v[48:51], v[164:167], v[202:205], v[48:51]
	v_mfma_f32_16x16x32_bf16 v[36:39], v[156:159], v[210:213], v[36:39]
	v_mfma_f32_16x16x32_bf16 v[32:35], v[164:167], v[210:213], v[32:35]
	v_mfma_f32_16x16x32_bf16 v[20:23], v[156:159], v[218:221], v[20:23]
	v_mfma_f32_16x16x32_bf16 v[16:19], v[164:167], v[218:221], v[16:19]
	v_mfma_f32_16x16x32_bf16 v[60:63], v[160:163], v[198:201], v[60:63]
	v_mfma_f32_16x16x32_bf16 v[56:59], v[168:171], v[198:201], v[56:59]
	v_mfma_f32_16x16x32_bf16 v[52:55], v[160:163], v[206:209], v[52:55]
	v_mfma_f32_16x16x32_bf16 v[48:51], v[168:171], v[206:209], v[48:51]
	v_mfma_f32_16x16x32_bf16 v[36:39], v[160:163], v[214:217], v[36:39]
	v_mfma_f32_16x16x32_bf16 v[32:35], v[168:171], v[214:217], v[32:35]
	v_mfma_f32_16x16x32_bf16 v[20:23], v[160:163], v[222:225], v[20:23]
	v_mfma_f32_16x16x32_bf16 v[16:19], v[168:171], v[222:225], v[16:19]
	s_setprio 0
	s_setprio 1
	v_mfma_f32_16x16x32_bf16 v[44:47], v[172:175], v[188:191], v[44:47]
	v_mfma_f32_16x16x32_bf16 v[40:43], v[180:183], v[188:191], v[40:43]
	v_mfma_f32_16x16x32_bf16 v[28:31], v[172:175], v[202:205], v[28:31]
	v_mfma_f32_16x16x32_bf16 v[24:27], v[180:183], v[202:205], v[24:27]
	v_mfma_f32_16x16x32_bf16 v[12:15], v[172:175], v[210:213], v[12:15]
	v_mfma_f32_16x16x32_bf16 v[8:11], v[180:183], v[210:213], v[8:11]
	v_mfma_f32_16x16x32_bf16 v[4:7], v[172:175], v[218:221], v[4:7]
	v_mfma_f32_16x16x32_bf16 v[0:3], v[180:183], v[218:221], v[0:3]
	v_mfma_f32_16x16x32_bf16 v[44:47], v[176:179], v[198:201], v[44:47]
	v_mfma_f32_16x16x32_bf16 v[40:43], v[184:187], v[198:201], v[40:43]
	v_mfma_f32_16x16x32_bf16 v[28:31], v[176:179], v[206:209], v[28:31]
	v_mfma_f32_16x16x32_bf16 v[24:27], v[184:187], v[206:209], v[24:27]
	v_mfma_f32_16x16x32_bf16 v[12:15], v[176:179], v[214:217], v[12:15]
	v_mfma_f32_16x16x32_bf16 v[8:11], v[184:187], v[214:217], v[8:11]
	v_mfma_f32_16x16x32_bf16 v[4:7], v[176:179], v[222:225], v[4:7]
	v_mfma_f32_16x16x32_bf16 v[0:3], v[184:187], v[222:225], v[0:3]
	s_setprio 0
	s_barrier
	s_add_i32 s27, 0, 0x18000
	s_add_i32 s52, 0, 0x1c000
	v_add_u32_e32 v168, s27, v139
	v_add_u32_e32 v184, s52, v139
	ds_read_b128 v[156:159], v168
	ds_read_b128 v[160:163], v168 offset:1024
	ds_read_b128 v[164:167], v168 offset:2048
	ds_read_b128 v[168:171], v168 offset:3072
	ds_read_b128 v[172:175], v184
	ds_read_b128 v[176:179], v184 offset:1024
	ds_read_b128 v[180:183], v184 offset:2048
	ds_read_b128 v[184:187], v184 offset:3072
	s_add_u32 s8, s18, 0x40000
	s_addc_u32 s9, s19, 0
	s_mov_b32 m0, s15
	v_lshl_add_u64 v[228:229], s[8:9], 0, v[128:129]
	ds_read_b128 v[188:191], v141 offset:32768
	ds_read_b128 v[198:201], v141 offset:33792
	ds_read_b128 v[202:205], v141 offset:34816
	ds_read_b128 v[206:209], v141 offset:35840
	ds_read_b128 v[210:213], v141 offset:36864
	ds_read_b128 v[214:217], v141 offset:37888
	ds_read_b128 v[218:221], v141 offset:38912
	ds_read_b128 v[222:225], v141 offset:39936
	global_load_lds_dwordx4 v[228:229], off
	v_lshl_add_u64 v[228:229], s[8:9], 0, v[130:131]
	s_mov_b32 m0, s23
	s_nop 0
	global_load_lds_dwordx4 v[228:229], off
	s_waitcnt vmcnt(8)
	s_waitcnt lgkmcnt(0)
	s_barrier
	s_setprio 1
	s_waitcnt lgkmcnt(0)
	v_mfma_f32_16x16x32_bf16 v[124:127], v[156:159], v[188:191], v[124:127]
	v_mfma_f32_16x16x32_bf16 v[120:123], v[164:167], v[188:191], v[120:123]
	v_mfma_f32_16x16x32_bf16 v[116:119], v[156:159], v[202:205], v[116:119]
	v_mfma_f32_16x16x32_bf16 v[112:115], v[164:167], v[202:205], v[112:115]
	v_mfma_f32_16x16x32_bf16 v[100:103], v[156:159], v[210:213], v[100:103]
	v_mfma_f32_16x16x32_bf16 v[96:99], v[164:167], v[210:213], v[96:99]
	v_mfma_f32_16x16x32_bf16 v[84:87], v[156:159], v[218:221], v[84:87]
	v_mfma_f32_16x16x32_bf16 v[80:83], v[164:167], v[218:221], v[80:83]
	v_mfma_f32_16x16x32_bf16 v[124:127], v[160:163], v[198:201], v[124:127]
	v_mfma_f32_16x16x32_bf16 v[120:123], v[168:171], v[198:201], v[120:123]
	v_mfma_f32_16x16x32_bf16 v[116:119], v[160:163], v[206:209], v[116:119]
	v_mfma_f32_16x16x32_bf16 v[112:115], v[168:171], v[206:209], v[112:115]
	v_mfma_f32_16x16x32_bf16 v[100:103], v[160:163], v[214:217], v[100:103]
	v_mfma_f32_16x16x32_bf16 v[96:99], v[168:171], v[214:217], v[96:99]
	v_mfma_f32_16x16x32_bf16 v[84:87], v[160:163], v[222:225], v[84:87]
	v_mfma_f32_16x16x32_bf16 v[80:83], v[168:171], v[222:225], v[80:83]
	s_setprio 0
	s_setprio 1
	v_mfma_f32_16x16x32_bf16 v[108:111], v[172:175], v[188:191], v[108:111]
	v_mfma_f32_16x16x32_bf16 v[104:107], v[180:183], v[188:191], v[104:107]
	v_mfma_f32_16x16x32_bf16 v[92:95], v[172:175], v[202:205], v[92:95]
	v_mfma_f32_16x16x32_bf16 v[88:91], v[180:183], v[202:205], v[88:91]
	v_mfma_f32_16x16x32_bf16 v[76:79], v[172:175], v[210:213], v[76:79]
	v_mfma_f32_16x16x32_bf16 v[72:75], v[180:183], v[210:213], v[72:75]
	v_mfma_f32_16x16x32_bf16 v[68:71], v[172:175], v[218:221], v[68:71]
	v_mfma_f32_16x16x32_bf16 v[64:67], v[180:183], v[218:221], v[64:67]
	v_mfma_f32_16x16x32_bf16 v[108:111], v[176:179], v[198:201], v[108:111]
	v_mfma_f32_16x16x32_bf16 v[104:107], v[184:187], v[198:201], v[104:107]
	v_mfma_f32_16x16x32_bf16 v[92:95], v[176:179], v[206:209], v[92:95]
	v_mfma_f32_16x16x32_bf16 v[88:91], v[184:187], v[206:209], v[88:91]
	v_mfma_f32_16x16x32_bf16 v[76:79], v[176:179], v[214:217], v[76:79]
	v_mfma_f32_16x16x32_bf16 v[72:75], v[184:187], v[214:217], v[72:75]
	v_mfma_f32_16x16x32_bf16 v[68:71], v[176:179], v[222:225], v[68:71]
	v_mfma_f32_16x16x32_bf16 v[64:67], v[184:187], v[222:225], v[64:67]
	s_setprio 0
	s_barrier
	s_add_i32 s8, s27, s16
	v_lshl_add_u64 v[142:143], v[142:143], 0, s[70:71]
	s_mov_b32 m0, s8
	ds_read_b128 v[188:191], v141 offset:49152
	ds_read_b128 v[198:201], v141 offset:50176
	ds_read_b128 v[202:205], v141 offset:51200
	ds_read_b128 v[206:209], v141 offset:52224
	ds_read_b128 v[210:213], v141 offset:53248
	ds_read_b128 v[214:217], v141 offset:54272
	ds_read_b128 v[218:221], v141 offset:55296
	ds_read_b128 v[222:225], v141 offset:56320
	global_load_lds_dwordx4 v[142:143], off
	s_add_i32 m0, s8, 0x2000
	s_add_u32 s8, s24, 0x40080
	v_lshl_add_u64 v[142:143], v[146:147], 0, s[70:71]
	s_addc_u32 s9, s25, 0
	s_add_i32 s18, s52, s16
	global_load_lds_dwordx4 v[142:143], off
	v_lshl_add_u64 v[142:143], s[8:9], 0, v[144:145]
	s_mov_b32 m0, s18
	s_nop 0
	global_load_lds_dwordx4 v[142:143], off
	v_lshl_add_u64 v[142:143], s[8:9], 0, v[132:133]
	s_add_i32 m0, s18, 0x2000
	s_nop 0
	global_load_lds_dwordx4 v[142:143], off
	v_lshl_add_u64 v[142:143], v[154:155], 0, s[70:71]
	s_mov_b32 m0, s0
	s_nop 0
	global_load_lds_dwordx4 v[142:143], off
	v_lshl_add_u64 v[142:143], v[226:227], 0, s[70:71]
	s_mov_b32 m0, s30
	s_nop 0
	global_load_lds_dwordx4 v[142:143], off
	s_waitcnt vmcnt(8)
	s_waitcnt lgkmcnt(0)
	s_barrier
	s_setprio 1
	s_waitcnt lgkmcnt(0)
	v_mfma_f32_16x16x32_bf16 v[60:63], v[156:159], v[188:191], v[60:63]
	v_mfma_f32_16x16x32_bf16 v[56:59], v[164:167], v[188:191], v[56:59]
	v_mfma_f32_16x16x32_bf16 v[52:55], v[156:159], v[202:205], v[52:55]
	v_mfma_f32_16x16x32_bf16 v[48:51], v[164:167], v[202:205], v[48:51]
	v_mfma_f32_16x16x32_bf16 v[36:39], v[156:159], v[210:213], v[36:39]
	v_mfma_f32_16x16x32_bf16 v[32:35], v[164:167], v[210:213], v[32:35]
	v_mfma_f32_16x16x32_bf16 v[20:23], v[156:159], v[218:221], v[20:23]
	v_mfma_f32_16x16x32_bf16 v[16:19], v[164:167], v[218:221], v[16:19]
	v_mfma_f32_16x16x32_bf16 v[60:63], v[160:163], v[198:201], v[60:63]
	v_mfma_f32_16x16x32_bf16 v[56:59], v[168:171], v[198:201], v[56:59]
	v_mfma_f32_16x16x32_bf16 v[52:55], v[160:163], v[206:209], v[52:55]
	v_mfma_f32_16x16x32_bf16 v[48:51], v[168:171], v[206:209], v[48:51]
	v_mfma_f32_16x16x32_bf16 v[36:39], v[160:163], v[214:217], v[36:39]
	v_mfma_f32_16x16x32_bf16 v[32:35], v[168:171], v[214:217], v[32:35]
	v_mfma_f32_16x16x32_bf16 v[20:23], v[160:163], v[222:225], v[20:23]
	v_mfma_f32_16x16x32_bf16 v[16:19], v[168:171], v[222:225], v[16:19]
	s_setprio 0
	s_setprio 1
	v_mfma_f32_16x16x32_bf16 v[44:47], v[172:175], v[188:191], v[44:47]
	s_add_i32 s51, s51, 2
	s_add_u32 s48, s48, 0x100
	s_addc_u32 s49, s49, 0
	s_add_u32 s43, s43, 0x100
	s_addc_u32 s50, s50, 0
	s_cmp_gt_u32 s51, 13
	v_mfma_f32_16x16x32_bf16 v[40:43], v[180:183], v[188:191], v[40:43]
	v_mfma_f32_16x16x32_bf16 v[28:31], v[172:175], v[202:205], v[28:31]
	v_mfma_f32_16x16x32_bf16 v[24:27], v[180:183], v[202:205], v[24:27]
	v_mfma_f32_16x16x32_bf16 v[12:15], v[172:175], v[210:213], v[12:15]
	v_mfma_f32_16x16x32_bf16 v[8:11], v[180:183], v[210:213], v[8:11]
	v_mfma_f32_16x16x32_bf16 v[4:7], v[172:175], v[218:221], v[4:7]
	v_mfma_f32_16x16x32_bf16 v[0:3], v[180:183], v[218:221], v[0:3]
	v_mfma_f32_16x16x32_bf16 v[44:47], v[176:179], v[198:201], v[44:47]
	v_mfma_f32_16x16x32_bf16 v[40:43], v[184:187], v[198:201], v[40:43]
	v_mfma_f32_16x16x32_bf16 v[28:31], v[176:179], v[206:209], v[28:31]
	v_mfma_f32_16x16x32_bf16 v[24:27], v[184:187], v[206:209], v[24:27]
	v_mfma_f32_16x16x32_bf16 v[12:15], v[176:179], v[214:217], v[12:15]
	v_mfma_f32_16x16x32_bf16 v[8:11], v[184:187], v[214:217], v[8:11]
	v_mfma_f32_16x16x32_bf16 v[4:7], v[176:179], v[222:225], v[4:7]
	v_mfma_f32_16x16x32_bf16 v[0:3], v[184:187], v[222:225], v[0:3]
	s_setprio 0
	s_barrier
	s_cbranch_scc0 .LBB0_1018
	s_and_b64 vcc, exec, s[12:13]
	s_movk_i32 s33, 0xe000
	s_cbranch_vccz .LBB0_1021
	s_barrier

.LBB0_1238:
	s_add_i32 s27, 0, 0x10000
	v_add_u32_e32 v146, s27, v143
	s_add_i32 s51, 0, 0x14000
	ds_read_b128 v[158:161], v146
	ds_read_b128 v[166:169], v146 offset:1024
	ds_read_b128 v[170:173], v146 offset:2048
	ds_read_b128 v[174:177], v146 offset:3072
	v_add_u32_e32 v146, s51, v143
	ds_read_b128 v[178:181], v146
	ds_read_b128 v[182:185], v146 offset:1024
	ds_read_b128 v[186:189], v146 offset:2048
	ds_read_b128 v[198:201], v146 offset:3072
	s_add_u32 s8, s42, s46
	s_addc_u32 s9, s43, s47
	s_add_u32 s8, s8, 0x100
	s_addc_u32 s9, s9, 0
	s_add_u32 s24, s48, s46
	s_addc_u32 s25, s49, s47
	s_cmpk_eq_i32 s46, 0x1500
	s_cselect_b32 s19, s45, s9
	s_cselect_b32 s18, s44, s8
	s_cselect_b32 s25, s41, s25
	s_cselect_b32 s24, s40, s24
	v_lshl_add_u64 v[146:147], v[138:139], 0, s[46:47]
	s_add_i32 m0, s3, 0xc000
	ds_read_b128 v[202:205], v156
	ds_read_b128 v[206:209], v156 offset:1024
	ds_read_b128 v[210:213], v156 offset:2048
	ds_read_b128 v[214:217], v156 offset:3072
	ds_read_b128 v[218:221], v156 offset:4096
	ds_read_b128 v[222:225], v156 offset:5120
	ds_read_b128 v[226:229], v156 offset:6144
	ds_read_b128 v[230:233], v156 offset:7168
	global_load_lds_dwordx4 v[146:147], off
	v_lshl_add_u64 v[146:147], v[140:141], 0, s[46:47]
	s_add_i32 m0, s3, 0xe000
	s_nop 0
	global_load_lds_dwordx4 v[146:147], off
	s_waitcnt vmcnt(8)
	s_waitcnt lgkmcnt(0)
	s_barrier
	s_setprio 1
	s_waitcnt lgkmcnt(0)
	v_mfma_f32_16x16x32_bf16 v[124:127], v[158:161], v[202:205], v[124:127]
	v_mfma_f32_16x16x32_bf16 v[120:123], v[170:173], v[202:205], v[120:123]
	v_mfma_f32_16x16x32_bf16 v[108:111], v[158:161], v[210:213], v[108:111]
	v_mfma_f32_16x16x32_bf16 v[104:107], v[170:173], v[210:213], v[104:107]
	v_mfma_f32_16x16x32_bf16 v[92:95], v[158:161], v[218:221], v[92:95]
	v_mfma_f32_16x16x32_bf16 v[88:91], v[170:173], v[218:221], v[88:91]
	v_mfma_f32_16x16x32_bf16 v[76:79], v[158:161], v[226:229], v[76:79]
	v_mfma_f32_16x16x32_bf16 v[72:75], v[170:173], v[226:229], v[72:75]
	v_mfma_f32_16x16x32_bf16 v[124:127], v[166:169], v[206:209], v[124:127]
	v_mfma_f32_16x16x32_bf16 v[120:123], v[174:177], v[206:209], v[120:123]
	v_mfma_f32_16x16x32_bf16 v[108:111], v[166:169], v[214:217], v[108:111]
	v_mfma_f32_16x16x32_bf16 v[104:107], v[174:177], v[214:217], v[104:107]
	v_mfma_f32_16x16x32_bf16 v[92:95], v[166:169], v[222:225], v[92:95]
	v_mfma_f32_16x16x32_bf16 v[88:91], v[174:177], v[222:225], v[88:91]
	v_mfma_f32_16x16x32_bf16 v[76:79], v[166:169], v[230:233], v[76:79]
	v_mfma_f32_16x16x32_bf16 v[72:75], v[174:177], v[230:233], v[72:75]
	s_setprio 0
	s_setprio 1
	v_mfma_f32_16x16x32_bf16 v[116:119], v[178:181], v[202:205], v[116:119]
	v_mfma_f32_16x16x32_bf16 v[112:115], v[186:189], v[202:205], v[112:115]
	v_mfma_f32_16x16x32_bf16 v[100:103], v[178:181], v[210:213], v[100:103]
	v_mfma_f32_16x16x32_bf16 v[96:99], v[186:189], v[210:213], v[96:99]
	v_mfma_f32_16x16x32_bf16 v[84:87], v[178:181], v[218:221], v[84:87]
	v_mfma_f32_16x16x32_bf16 v[80:83], v[186:189], v[218:221], v[80:83]
	v_mfma_f32_16x16x32_bf16 v[68:71], v[178:181], v[226:229], v[68:71]
	v_mfma_f32_16x16x32_bf16 v[64:67], v[186:189], v[226:229], v[64:67]
	v_mfma_f32_16x16x32_bf16 v[116:119], v[182:185], v[206:209], v[116:119]
	v_mfma_f32_16x16x32_bf16 v[112:115], v[198:201], v[206:209], v[112:115]
	v_mfma_f32_16x16x32_bf16 v[100:103], v[182:185], v[214:217], v[100:103]
	v_mfma_f32_16x16x32_bf16 v[96:99], v[198:201], v[214:217], v[96:99]
	v_mfma_f32_16x16x32_bf16 v[84:87], v[182:185], v[222:225], v[84:87]
	v_mfma_f32_16x16x32_bf16 v[80:83], v[198:201], v[222:225], v[80:83]
	v_mfma_f32_16x16x32_bf16 v[68:71], v[182:185], v[230:233], v[68:71]
	v_mfma_f32_16x16x32_bf16 v[64:67], v[198:201], v[230:233], v[64:67]
	s_setprio 0
	s_barrier
	s_add_i32 s8, s27, s2
	v_lshl_add_u64 v[146:147], s[24:25], 0, v[144:145]
	s_mov_b32 m0, s8
	ds_read_b128 v[202:205], v156 offset:16384
	ds_read_b128 v[206:209], v156 offset:17408
	ds_read_b128 v[210:213], v156 offset:18432
	ds_read_b128 v[214:217], v156 offset:19456
	ds_read_b128 v[218:221], v156 offset:20480
	ds_read_b128 v[222:225], v156 offset:21504
	ds_read_b128 v[226:229], v156 offset:22528
	ds_read_b128 v[230:233], v156 offset:23552
	global_load_lds_dwordx4 v[146:147], off
	s_add_i32 m0, s8, 0x2000
	s_add_u32 s8, s24, 0xb0000
	v_lshl_add_u64 v[154:155], s[24:25], 0, v[128:129]
	s_addc_u32 s9, s25, 0
	s_add_i32 s27, s51, s2
	global_load_lds_dwordx4 v[154:155], off
	v_lshl_add_u64 v[190:191], s[8:9], 0, v[144:145]
	s_mov_b32 m0, s27
	v_lshl_add_u64 v[234:235], s[18:19], 0, v[130:131]
	global_load_lds_dwordx4 v[190:191], off
	v_lshl_add_u64 v[190:191], s[8:9], 0, v[128:129]
	s_add_i32 m0, s27, 0x2000
	s_nop 0
	global_load_lds_dwordx4 v[190:191], off
	v_lshl_add_u64 v[190:191], s[18:19], 0, v[132:133]
	s_mov_b32 m0, s3
	s_nop 0
	global_load_lds_dwordx4 v[190:191], off
	s_mov_b32 m0, s4
	s_nop 0
	global_load_lds_dwordx4 v[234:235], off
	s_waitcnt vmcnt(8)
	s_waitcnt lgkmcnt(0)
	s_barrier
	s_setprio 1
	s_waitcnt lgkmcnt(0)
	v_mfma_f32_16x16x32_bf16 v[60:63], v[158:161], v[202:205], v[60:63]
	v_mfma_f32_16x16x32_bf16 v[56:59], v[170:173], v[202:205], v[56:59]
	v_mfma_f32_16x16x32_bf16 v[44:47], v[158:161], v[210:213], v[44:47]
	v_mfma_f32_16x16x32_bf16 v[40:43], v[170:173], v[210:213], v[40:43]
	v_mfma_f32_16x16x32_bf16 v[28:31], v[158:161], v[218:221], v[28:31]
	v_mfma_f32_16x16x32_bf16 v[24:27], v[170:173], v[218:221], v[24:27]
	v_mfma_f32_16x16x32_bf16 v[12:15], v[158:161], v[226:229], v[12:15]
	v_mfma_f32_16x16x32_bf16 v[8:11], v[170:173], v[226:229], v[8:11]
	v_mfma_f32_16x16x32_bf16 v[60:63], v[166:169], v[206:209], v[60:63]
	v_mfma_f32_16x16x32_bf16 v[56:59], v[174:177], v[206:209], v[56:59]
	v_mfma_f32_16x16x32_bf16 v[44:47], v[166:169], v[214:217], v[44:47]
	v_mfma_f32_16x16x32_bf16 v[40:43], v[174:177], v[214:217], v[40:43]
	v_mfma_f32_16x16x32_bf16 v[28:31], v[166:169], v[222:225], v[28:31]
	v_mfma_f32_16x16x32_bf16 v[24:27], v[174:177], v[222:225], v[24:27]
	v_mfma_f32_16x16x32_bf16 v[12:15], v[166:169], v[230:233], v[12:15]
	v_mfma_f32_16x16x32_bf16 v[8:11], v[174:177], v[230:233], v[8:11]
	s_setprio 0
	s_setprio 1
	v_mfma_f32_16x16x32_bf16 v[52:55], v[178:181], v[202:205], v[52:55]
	v_mfma_f32_16x16x32_bf16 v[48:51], v[186:189], v[202:205], v[48:51]
	v_mfma_f32_16x16x32_bf16 v[36:39], v[178:181], v[210:213], v[36:39]
	v_mfma_f32_16x16x32_bf16 v[32:35], v[186:189], v[210:213], v[32:35]
	v_mfma_f32_16x16x32_bf16 v[20:23], v[178:181], v[218:221], v[20:23]
	v_mfma_f32_16x16x32_bf16 v[16:19], v[186:189], v[218:221], v[16:19]
	v_mfma_f32_16x16x32_bf16 v[4:7], v[178:181], v[226:229], v[4:7]
	v_mfma_f32_16x16x32_bf16 v[0:3], v[186:189], v[226:229], v[0:3]
	v_mfma_f32_16x16x32_bf16 v[52:55], v[182:185], v[206:209], v[52:55]
	v_mfma_f32_16x16x32_bf16 v[48:51], v[198:201], v[206:209], v[48:51]
	v_mfma_f32_16x16x32_bf16 v[36:39], v[182:185], v[214:217], v[36:39]
	v_mfma_f32_16x16x32_bf16 v[32:35], v[198:201], v[214:217], v[32:35]
	v_mfma_f32_16x16x32_bf16 v[20:23], v[182:185], v[222:225], v[20:23]
	v_mfma_f32_16x16x32_bf16 v[16:19], v[198:201], v[222:225], v[16:19]
	v_mfma_f32_16x16x32_bf16 v[4:7], v[182:185], v[230:233], v[4:7]
	v_mfma_f32_16x16x32_bf16 v[0:3], v[198:201], v[230:233], v[0:3]
	s_setprio 0
	s_barrier
	s_add_i32 s27, 0, 0x18000
	v_add_u32_e32 v157, s27, v143
	s_add_i32 s51, 0, 0x1c000
	ds_read_b128 v[158:161], v157
	ds_read_b128 v[166:169], v157 offset:1024
	ds_read_b128 v[170:173], v157 offset:2048
	ds_read_b128 v[174:177], v157 offset:3072
	v_add_u32_e32 v157, s51, v143
	ds_read_b128 v[178:181], v157
	ds_read_b128 v[182:185], v157 offset:1024
	ds_read_b128 v[186:189], v157 offset:2048
	ds_read_b128 v[198:201], v157 offset:3072
	s_add_u32 s8, s18, 0xc0000
	s_addc_u32 s9, s19, 0
	s_mov_b32 m0, s5
	v_lshl_add_u64 v[236:237], s[8:9], 0, v[132:133]
	ds_read_b128 v[202:205], v156 offset:32768
	ds_read_b128 v[206:209], v156 offset:33792
	ds_read_b128 v[210:213], v156 offset:34816
	ds_read_b128 v[214:217], v156 offset:35840
	ds_read_b128 v[218:221], v156 offset:36864
	ds_read_b128 v[222:225], v156 offset:37888
	ds_read_b128 v[226:229], v156 offset:38912
	ds_read_b128 v[230:233], v156 offset:39936
	global_load_lds_dwordx4 v[236:237], off
	v_lshl_add_u64 v[236:237], s[8:9], 0, v[130:131]
	s_mov_b32 m0, s14
	s_nop 0
	global_load_lds_dwordx4 v[236:237], off
	s_waitcnt vmcnt(8)
	s_waitcnt lgkmcnt(0)
	s_barrier
	s_setprio 1
	s_waitcnt lgkmcnt(0)
	v_mfma_f32_16x16x32_bf16 v[124:127], v[158:161], v[202:205], v[124:127]
	v_mfma_f32_16x16x32_bf16 v[120:123], v[170:173], v[202:205], v[120:123]
	v_mfma_f32_16x16x32_bf16 v[108:111], v[158:161], v[210:213], v[108:111]
	v_mfma_f32_16x16x32_bf16 v[104:107], v[170:173], v[210:213], v[104:107]
	v_mfma_f32_16x16x32_bf16 v[92:95], v[158:161], v[218:221], v[92:95]
	v_mfma_f32_16x16x32_bf16 v[88:91], v[170:173], v[218:221], v[88:91]
	v_mfma_f32_16x16x32_bf16 v[76:79], v[158:161], v[226:229], v[76:79]
	v_mfma_f32_16x16x32_bf16 v[72:75], v[170:173], v[226:229], v[72:75]
	v_mfma_f32_16x16x32_bf16 v[124:127], v[166:169], v[206:209], v[124:127]
	v_mfma_f32_16x16x32_bf16 v[120:123], v[174:177], v[206:209], v[120:123]
	v_mfma_f32_16x16x32_bf16 v[108:111], v[166:169], v[214:217], v[108:111]
	v_mfma_f32_16x16x32_bf16 v[104:107], v[174:177], v[214:217], v[104:107]
	v_mfma_f32_16x16x32_bf16 v[92:95], v[166:169], v[222:225], v[92:95]
	v_mfma_f32_16x16x32_bf16 v[88:91], v[174:177], v[222:225], v[88:91]
	v_mfma_f32_16x16x32_bf16 v[76:79], v[166:169], v[230:233], v[76:79]
	v_mfma_f32_16x16x32_bf16 v[72:75], v[174:177], v[230:233], v[72:75]
	s_setprio 0
	s_setprio 1
	v_mfma_f32_16x16x32_bf16 v[116:119], v[178:181], v[202:205], v[116:119]
	v_mfma_f32_16x16x32_bf16 v[112:115], v[186:189], v[202:205], v[112:115]
	v_mfma_f32_16x16x32_bf16 v[100:103], v[178:181], v[210:213], v[100:103]
	v_mfma_f32_16x16x32_bf16 v[96:99], v[186:189], v[210:213], v[96:99]
	v_mfma_f32_16x16x32_bf16 v[84:87], v[178:181], v[218:221], v[84:87]
	v_mfma_f32_16x16x32_bf16 v[80:83], v[186:189], v[218:221], v[80:83]
	v_mfma_f32_16x16x32_bf16 v[68:71], v[178:181], v[226:229], v[68:71]
	v_mfma_f32_16x16x32_bf16 v[64:67], v[186:189], v[226:229], v[64:67]
	v_mfma_f32_16x16x32_bf16 v[116:119], v[182:185], v[206:209], v[116:119]
	v_mfma_f32_16x16x32_bf16 v[112:115], v[198:201], v[206:209], v[112:115]
	v_mfma_f32_16x16x32_bf16 v[100:103], v[182:185], v[214:217], v[100:103]
	v_mfma_f32_16x16x32_bf16 v[96:99], v[198:201], v[214:217], v[96:99]
	v_mfma_f32_16x16x32_bf16 v[84:87], v[182:185], v[222:225], v[84:87]
	v_mfma_f32_16x16x32_bf16 v[80:83], v[198:201], v[222:225], v[80:83]
	v_mfma_f32_16x16x32_bf16 v[68:71], v[182:185], v[230:233], v[68:71]
	v_mfma_f32_16x16x32_bf16 v[64:67], v[198:201], v[230:233], v[64:67]
	s_setprio 0
	s_barrier
	s_add_i32 s8, s27, s2
	v_lshl_add_u64 v[146:147], v[146:147], 0, s[70:71]
	s_mov_b32 m0, s8
	ds_read_b128 v[202:205], v156 offset:49152
	ds_read_b128 v[206:209], v156 offset:50176
	ds_read_b128 v[210:213], v156 offset:51200
	ds_read_b128 v[214:217], v156 offset:52224
	ds_read_b128 v[218:221], v156 offset:53248
	ds_read_b128 v[222:225], v156 offset:54272
	ds_read_b128 v[226:229], v156 offset:55296
	ds_read_b128 v[230:233], v156 offset:56320
	global_load_lds_dwordx4 v[146:147], off
	s_add_i32 m0, s8, 0x2000
	s_add_u32 s8, s24, 0xb0080
	v_lshl_add_u64 v[146:147], v[154:155], 0, s[70:71]
	s_addc_u32 s9, s25, 0
	s_add_i32 s18, s51, s2
	global_load_lds_dwordx4 v[146:147], off
	v_lshl_add_u64 v[146:147], s[8:9], 0, v[144:145]
	s_mov_b32 m0, s18
	s_nop 0
	global_load_lds_dwordx4 v[146:147], off
	v_lshl_add_u64 v[146:147], s[8:9], 0, v[128:129]
	s_add_i32 m0, s18, 0x2000
	s_nop 0
	global_load_lds_dwordx4 v[146:147], off
	v_lshl_add_u64 v[146:147], v[190:191], 0, s[70:71]
	s_mov_b32 m0, s10
	s_nop 0
	global_load_lds_dwordx4 v[146:147], off
	v_lshl_add_u64 v[146:147], v[234:235], 0, s[70:71]
	s_mov_b32 m0, s11
	s_nop 0
	global_load_lds_dwordx4 v[146:147], off
	s_waitcnt vmcnt(8)
	s_waitcnt lgkmcnt(0)
	s_barrier
	s_setprio 1
	s_waitcnt lgkmcnt(0)
	v_mfma_f32_16x16x32_bf16 v[60:63], v[158:161], v[202:205], v[60:63]
	v_mfma_f32_16x16x32_bf16 v[56:59], v[170:173], v[202:205], v[56:59]
	v_mfma_f32_16x16x32_bf16 v[44:47], v[158:161], v[210:213], v[44:47]
	v_mfma_f32_16x16x32_bf16 v[40:43], v[170:173], v[210:213], v[40:43]
	v_mfma_f32_16x16x32_bf16 v[28:31], v[158:161], v[218:221], v[28:31]
	v_mfma_f32_16x16x32_bf16 v[24:27], v[170:173], v[218:221], v[24:27]
	v_mfma_f32_16x16x32_bf16 v[12:15], v[158:161], v[226:229], v[12:15]
	v_mfma_f32_16x16x32_bf16 v[8:11], v[170:173], v[226:229], v[8:11]
	v_mfma_f32_16x16x32_bf16 v[60:63], v[166:169], v[206:209], v[60:63]
	v_mfma_f32_16x16x32_bf16 v[56:59], v[174:177], v[206:209], v[56:59]
	v_mfma_f32_16x16x32_bf16 v[44:47], v[166:169], v[214:217], v[44:47]
	v_mfma_f32_16x16x32_bf16 v[40:43], v[174:177], v[214:217], v[40:43]
	v_mfma_f32_16x16x32_bf16 v[28:31], v[166:169], v[222:225], v[28:31]
	v_mfma_f32_16x16x32_bf16 v[24:27], v[174:177], v[222:225], v[24:27]
	v_mfma_f32_16x16x32_bf16 v[12:15], v[166:169], v[230:233], v[12:15]
	v_mfma_f32_16x16x32_bf16 v[8:11], v[174:177], v[230:233], v[8:11]
	s_setprio 0
	s_setprio 1
	v_mfma_f32_16x16x32_bf16 v[52:55], v[178:181], v[202:205], v[52:55]
	s_add_i32 s50, s50, 2
	s_add_u32 s46, s46, 0x100
	s_addc_u32 s47, s47, 0
	s_cmp_gt_u32 s50, 41
	v_mfma_f32_16x16x32_bf16 v[48:51], v[186:189], v[202:205], v[48:51]
	v_mfma_f32_16x16x32_bf16 v[36:39], v[178:181], v[210:213], v[36:39]
	v_mfma_f32_16x16x32_bf16 v[32:35], v[186:189], v[210:213], v[32:35]
	v_mfma_f32_16x16x32_bf16 v[20:23], v[178:181], v[218:221], v[20:23]
	v_mfma_f32_16x16x32_bf16 v[16:19], v[186:189], v[218:221], v[16:19]
	v_mfma_f32_16x16x32_bf16 v[4:7], v[178:181], v[226:229], v[4:7]
	v_mfma_f32_16x16x32_bf16 v[0:3], v[186:189], v[226:229], v[0:3]
	v_mfma_f32_16x16x32_bf16 v[52:55], v[182:185], v[206:209], v[52:55]
	v_mfma_f32_16x16x32_bf16 v[48:51], v[198:201], v[206:209], v[48:51]
	v_mfma_f32_16x16x32_bf16 v[36:39], v[182:185], v[214:217], v[36:39]
	v_mfma_f32_16x16x32_bf16 v[32:35], v[198:201], v[214:217], v[32:35]
	v_mfma_f32_16x16x32_bf16 v[20:23], v[182:185], v[222:225], v[20:23]
	v_mfma_f32_16x16x32_bf16 v[16:19], v[198:201], v[222:225], v[16:19]
	v_mfma_f32_16x16x32_bf16 v[4:7], v[182:185], v[230:233], v[4:7]
	v_mfma_f32_16x16x32_bf16 v[0:3], v[198:201], v[230:233], v[0:3]
	s_setprio 0
	s_barrier
	s_cbranch_scc0 .LBB0_1238
	s_add_u32 s18, s48, 0xffffff00
	s_addc_u32 s19, s49, -1
	s_and_b64 vcc, exec, s[38:39]
	s_cbranch_vccnz .LBB0_1241
	v_mov_b32_e32 v0, 0
	s_mov_b32 s12, s30
	s_mov_b32 s23, s31
	s_mov_b64 s[42:43], s[44:45]
	s_mov_b32 s16, s33
	v_mov_b32_e32 v1, v0
	v_mov_b32_e32 v2, v0
	v_mov_b32_e32 v3, v0
	v_mov_b32_e32 v4, v0
	v_mov_b32_e32 v5, v0
	v_mov_b32_e32 v6, v0
	v_mov_b32_e32 v7, v0
	v_mov_b32_e32 v16, v0
	v_mov_b32_e32 v17, v0
	v_mov_b32_e32 v18, v0
	v_mov_b32_e32 v19, v0
	v_mov_b32_e32 v20, v0
	v_mov_b32_e32 v21, v0
	v_mov_b32_e32 v22, v0
	v_mov_b32_e32 v23, v0
	v_mov_b32_e32 v32, v0
	v_mov_b32_e32 v33, v0
	v_mov_b32_e32 v34, v0
	v_mov_b32_e32 v35, v0
	v_mov_b32_e32 v36, v0
	v_mov_b32_e32 v37, v0
	v_mov_b32_e32 v38, v0
	v_mov_b32_e32 v39, v0
	v_mov_b32_e32 v48, v0
	v_mov_b32_e32 v49, v0
	v_mov_b32_e32 v50, v0
	v_mov_b32_e32 v51, v0
	v_mov_b32_e32 v52, v0
	v_mov_b32_e32 v53, v0
	v_mov_b32_e32 v54, v0
	v_mov_b32_e32 v55, v0
	v_mov_b32_e32 v8, v0
	v_mov_b32_e32 v9, v0
	v_mov_b32_e32 v10, v0
	v_mov_b32_e32 v11, v0
	v_mov_b32_e32 v12, v0
	v_mov_b32_e32 v13, v0
	v_mov_b32_e32 v14, v0
	v_mov_b32_e32 v15, v0
	v_mov_b32_e32 v24, v0
	v_mov_b32_e32 v25, v0
	v_mov_b32_e32 v26, v0
	v_mov_b32_e32 v27, v0
	v_mov_b32_e32 v28, v0
	v_mov_b32_e32 v29, v0
	v_mov_b32_e32 v30, v0
	v_mov_b32_e32 v31, v0
	v_mov_b32_e32 v40, v0
	v_mov_b32_e32 v41, v0
	v_mov_b32_e32 v42, v0
	v_mov_b32_e32 v43, v0
	v_mov_b32_e32 v44, v0
	v_mov_b32_e32 v45, v0
	v_mov_b32_e32 v46, v0
	v_mov_b32_e32 v47, v0
	v_mov_b32_e32 v56, v0
	v_mov_b32_e32 v57, v0
	v_mov_b32_e32 v58, v0
	v_mov_b32_e32 v59, v0
	v_mov_b32_e32 v60, v0
	v_mov_b32_e32 v61, v0
	v_mov_b32_e32 v62, v0
	v_mov_b32_e32 v63, v0
	v_mov_b32_e32 v64, v0
	v_mov_b32_e32 v65, v0
	v_mov_b32_e32 v66, v0
	v_mov_b32_e32 v67, v0
	v_mov_b32_e32 v68, v0
	v_mov_b32_e32 v69, v0
	v_mov_b32_e32 v70, v0
	v_mov_b32_e32 v71, v0
	v_mov_b32_e32 v80, v0
	v_mov_b32_e32 v81, v0
	v_mov_b32_e32 v82, v0
	v_mov_b32_e32 v83, v0
	v_mov_b32_e32 v84, v0
	v_mov_b32_e32 v85, v0
	v_mov_b32_e32 v86, v0
	v_mov_b32_e32 v87, v0
	v_mov_b32_e32 v96, v0
	v_mov_b32_e32 v97, v0
	v_mov_b32_e32 v98, v0
	v_mov_b32_e32 v99, v0
	v_mov_b32_e32 v100, v0
	v_mov_b32_e32 v101, v0
	v_mov_b32_e32 v102, v0
	v_mov_b32_e32 v103, v0
	v_mov_b32_e32 v112, v0
	v_mov_b32_e32 v113, v0
	v_mov_b32_e32 v114, v0
	v_mov_b32_e32 v115, v0
	v_mov_b32_e32 v116, v0
	v_mov_b32_e32 v117, v0
	v_mov_b32_e32 v118, v0
	v_mov_b32_e32 v119, v0
	v_mov_b32_e32 v72, v0
	v_mov_b32_e32 v73, v0
	v_mov_b32_e32 v74, v0
	v_mov_b32_e32 v75, v0
	v_mov_b32_e32 v76, v0
	v_mov_b32_e32 v77, v0
	v_mov_b32_e32 v78, v0
	v_mov_b32_e32 v79, v0
	v_mov_b32_e32 v88, v0
	v_mov_b32_e32 v89, v0
	v_mov_b32_e32 v90, v0
	v_mov_b32_e32 v91, v0
	v_mov_b32_e32 v92, v0
	v_mov_b32_e32 v93, v0
	v_mov_b32_e32 v94, v0
	v_mov_b32_e32 v95, v0
	v_mov_b32_e32 v104, v0
	v_mov_b32_e32 v105, v0
	v_mov_b32_e32 v106, v0
	v_mov_b32_e32 v107, v0
	v_mov_b32_e32 v108, v0
	v_mov_b32_e32 v109, v0
	v_mov_b32_e32 v110, v0
	v_mov_b32_e32 v111, v0
	v_mov_b32_e32 v120, v0
	v_mov_b32_e32 v121, v0
	v_mov_b32_e32 v122, v0
	v_mov_b32_e32 v123, v0
	v_mov_b32_e32 v124, v0
	v_mov_b32_e32 v125, v0
	v_mov_b32_e32 v126, v0
	v_mov_b32_e32 v127, v0
	s_branch .LBB0_1242
